# grid barriers after P3 P4 P7 P8 now only synchronise the 32 workgroups that own the same 1024 token rows (group-local rows in P1 P4 P7 P9, write-through stores for the handed-over data)
# speedup vs baseline: 1.0041x; 1.0041x over previous
.LBB0_193:
	v_readlane_b32 s4, v254, 0
	v_readlane_b32 s5, v254, 1
	s_cmp_lt_i32 s4, 2
	s_cselect_b64 s[4:5], -1, 0
	s_and_b64 s[4:5], s[4:5], s[0:1]
	s_andn2_b64 vcc, exec, s[4:5]
	s_cbranch_vccnz .LBB0_197
	s_cmpk_gt_i32 s70, 0x1fff
	s_cbranch_scc1 .LBB0_197
	s_mov_b32 s98, s70
	s_movk_i32 s100, 0x2000
	s_mov_b32 s101, s72
	s_cmpk_lg_i32 s3, 0x100
	s_cbranch_scc1 .Lmy_gr1
	s_and_b32 s98, s2, 7
	s_lshl_b32 s98, s98, 10
	s_add_i32 s100, s98, 0x400
	s_lshr_b32 s99, s2, 3
	s_lshl_b32 s99, s99, 3
	s_add_i32 s98, s98, s99
	v_readlane_b32 s99, v254, 10
	s_add_i32 s98, s98, s99
	s_movk_i32 s101, 0x100
.Lmy_gr1:
	s_mov_b32 s99, 0
	v_lshlrev_b32_e32 v34, 2, v1
	v_or_b32_e32 v36, 0x400, v34
	v_or_b32_e32 v38, 0x500, v34
	v_or_b32_e32 v40, 0x600, v34
	v_or_b32_e32 v42, 0x700, v34
	v_lshlrev_b32_e32 v44, 4, v1
	v_lshlrev_b32_e32 v35, 2, v42
	v_lshlrev_b32_e32 v37, 2, v40
	v_lshlrev_b32_e32 v39, 2, v38
	v_lshlrev_b32_e32 v41, 2, v36
	s_waitcnt lgkmcnt(0)
	global_load_dwordx4 v[2:5], v44, s[16:17]
	global_load_dwordx4 v[6:9], v44, s[16:17] offset:1024
	global_load_dwordx4 v[10:13], v44, s[16:17] offset:2048
	global_load_dwordx4 v[14:17], v44, s[16:17] offset:3072
	global_load_dwordx4 v[18:21], v41, s[16:17]
	global_load_dwordx4 v[22:25], v39, s[16:17]
	global_load_dwordx4 v[26:29], v37, s[16:17]
	global_load_dwordx4 v[30:33], v35, s[16:17]
	v_mbcnt_lo_u32_b32 v35, -1, 0
	v_mbcnt_hi_u32_b32 v35, -1, v35
	v_and_b32_e32 v37, 64, v35
	v_add_u32_e32 v37, 64, v37
	v_xor_b32_e32 v39, 1, v35
	v_cmp_lt_i32_e32 vcc, v39, v37
	s_ashr_i32 s71, s70, 31
	s_lshl_b64 s[0:1], s[98:99], 13
	v_cndmask_b32_e32 v39, v35, v39, vcc
	v_lshlrev_b32_e32 v62, 2, v39
	v_xor_b32_e32 v39, 2, v35
	v_cmp_lt_i32_e32 vcc, v39, v37
	s_add_u32 s0, s8, s0
	v_mov_b32_e32 v45, 0
	v_cndmask_b32_e32 v39, v35, v39, vcc
	v_lshlrev_b32_e32 v63, 2, v39
	v_xor_b32_e32 v39, 4, v35
	v_cmp_lt_i32_e32 vcc, v39, v37
	s_addc_u32 s1, s9, s1
	v_lshl_add_u64 v[52:53], s[0:1], 0, v[44:45]
	v_cndmask_b32_e32 v39, v35, v39, vcc
	v_lshlrev_b32_e32 v64, 2, v39
	v_xor_b32_e32 v39, 8, v35
	v_cmp_lt_i32_e32 vcc, v39, v37
	s_mov_b64 s[0:1], 0x1000
	s_ashr_i32 s73, s72, 31
	v_cndmask_b32_e32 v39, v35, v39, vcc
	v_lshlrev_b32_e32 v65, 2, v39
	v_xor_b32_e32 v39, 16, v35
	v_cmp_lt_i32_e32 vcc, v39, v37
	v_lshl_add_u64 v[58:59], v[52:53], 0, s[0:1]
	s_lshl_b32 s0, s101, 13
	s_mov_b32 s1, 0
	v_cndmask_b32_e32 v39, v35, v39, vcc
	s_lshl_b64 s[6:7], s[98:99], 12
	v_lshlrev_b32_e32 v66, 2, v39
	v_xor_b32_e32 v39, 32, v35
	s_add_u32 s6, s50, s6
	v_cmp_lt_i32_e32 vcc, v39, v37
	v_lshlrev_b32_e32 v44, 3, v1
	s_addc_u32 s7, s51, s7
	v_or_b32_e32 v46, 0x100, v34
	v_or_b32_e32 v48, 0x200, v34
	v_or_b32_e32 v50, 0x300, v34
	v_cndmask_b32_e32 v35, v35, v39, vcc
	v_lshl_add_u64 v[44:45], s[6:7], 0, v[44:45]
	s_mov_b64 s[6:7], 0xac00000
	v_lshlrev_b32_e32 v67, 2, v35
	v_lshl_add_u64 v[60:61], v[44:45], 0, s[6:7]
	s_lshl_b32 s6, s101, 12
	s_mov_b32 s7, 0
	v_mov_b32_e32 v68, 0x358637bd
	v_lshlrev_b32_e32 v69, 2, v34
	v_lshlrev_b32_e32 v70, 2, v46
	v_lshlrev_b32_e32 v71, 2, v48
	v_lshlrev_b32_e32 v72, 2, v50
	v_lshlrev_b32_e32 v73, 2, v36
	v_lshlrev_b32_e32 v74, 2, v38
	v_lshlrev_b32_e32 v75, 2, v40
	v_lshlrev_b32_e32 v76, 2, v42
	s_mov_b32 s14, s98
.LBB0_196:
	global_load_dwordx4 v[46:49], v[58:59], off offset:-2048 nt
	global_load_dwordx4 v[38:41], v[58:59], off offset:1024 nt
	global_load_dwordx4 v[78:81], v[58:59], off offset:-4096 nt
	global_load_dwordx4 v[82:85], v[58:59], off offset:-3072 nt
	global_load_dwordx4 v[54:57], v[58:59], off offset:-1024 nt
	global_load_dwordx4 v[50:53], v[58:59], off nt
	global_load_dwordx4 v[42:45], v[58:59], off offset:2048 nt
	global_load_dwordx4 v[34:37], v[58:59], off offset:3072 nt
	s_ashr_i32 s10, s14, 12
	s_mul_hi_i32 s11, s10, 0x12000
	s_mul_i32 s10, s10, 0x12000
	s_add_u32 s10, s50, s10
	s_addc_u32 s11, s51, s11
	s_add_u32 s12, s10, 0x2000
	s_addc_u32 s13, s11, 0
	global_load_dwordx4 v[86:89], v69, s[12:13]
	global_load_dwordx4 v[90:93], v69, s[10:11]
	s_add_i32 s14, s14, s101
	v_lshl_add_u64 v[58:59], v[58:59], 0, s[0:1]
	s_cmp_lt_i32 s14, s100
	s_waitcnt vmcnt(9)
	v_pk_mul_f32 v[94:95], v[48:49], v[48:49]
	v_pk_mul_f32 v[96:97], v[46:47], v[46:47]
	s_waitcnt vmcnt(8)
	v_pk_mul_f32 v[98:99], v[40:41], v[40:41]
	v_pk_mul_f32 v[100:101], v[38:39], v[38:39]
	s_waitcnt vmcnt(7)
	v_mov_b32_e32 v104, v79
	s_waitcnt vmcnt(6)
	v_mov_b32_e32 v105, v83
	v_mov_b32_e32 v108, v81
	v_mov_b32_e32 v109, v85
	v_mov_b32_e32 v102, v78
	v_mov_b32_e32 v103, v82
	v_mov_b32_e32 v106, v80
	v_mov_b32_e32 v107, v84
	v_pk_mov_b32 v[118:119], v[96:97], v[94:95] op_sel:[1,0]
	v_mov_b32_e32 v97, v95
	v_pk_mov_b32 v[94:95], v[100:101], v[98:99] op_sel:[1,0]
	v_mov_b32_e32 v101, v99
	v_pk_mul_f32 v[98:99], v[104:105], v[104:105]
	v_pk_mul_f32 v[104:105], v[108:109], v[108:109]
	v_pk_fma_f32 v[98:99], v[102:103], v[102:103], v[98:99]
	v_pk_fma_f32 v[102:103], v[106:107], v[106:107], v[104:105]
	s_waitcnt vmcnt(5)
	v_mul_f32_e32 v110, v55, v55
	v_mul_f32_e32 v112, v57, v57
	v_pk_add_f32 v[96:97], v[118:119], v[96:97]
	v_pk_add_f32 v[98:99], v[98:99], v[102:103]
	s_waitcnt vmcnt(4)
	v_mul_f32_e32 v77, v52, v52
	v_mul_f32_e32 v117, v53, v53
	v_mul_f32_e32 v122, v51, v51
	v_mul_f32_e32 v123, v50, v50
	v_pk_fma_f32 v[108:109], v[54:55], v[54:55], v[110:111] op_sel_hi:[1,1,0]
	v_pk_fma_f32 v[110:111], v[56:57], v[56:57], v[112:113] op_sel_hi:[1,1,0]
	v_pk_add_f32 v[96:97], v[96:97], v[96:97] op_sel:[0,1] op_sel_hi:[1,0]
	v_pk_add_f32 v[98:99], v[98:99], v[98:99] op_sel:[0,1] op_sel_hi:[1,0]
	v_mov_b32_e32 v109, v77
	v_mov_b32_e32 v111, v117
	v_mov_b32_e32 v97, v122
	v_mov_b32_e32 v99, v123
	v_pk_add_f32 v[94:95], v[94:95], v[100:101]
	v_pk_add_f32 v[100:101], v[108:109], v[110:111]
	v_pk_add_f32 v[96:97], v[98:99], v[96:97]
	s_waitcnt vmcnt(3)
	v_mul_f32_e32 v114, v43, v43
	v_mul_f32_e32 v116, v45, v45
	v_pk_add_f32 v[96:97], v[96:97], v[100:101]
	s_waitcnt vmcnt(2)
	v_mul_f32_e32 v120, v36, v36
	v_mul_f32_e32 v121, v37, v37
	v_mul_f32_e32 v124, v35, v35
	v_mul_f32_e32 v125, v34, v34
	v_pk_fma_f32 v[112:113], v[42:43], v[42:43], v[114:115] op_sel_hi:[1,1,0]
	v_pk_fma_f32 v[114:115], v[44:45], v[44:45], v[116:117] op_sel_hi:[1,1,0]
	v_pk_add_f32 v[94:95], v[94:95], v[94:95] op_sel:[0,1] op_sel_hi:[1,0]
	v_pk_add_f32 v[96:97], v[96:97], v[96:97] op_sel:[0,1] op_sel_hi:[1,0]
	v_mov_b32_e32 v113, v120
	v_mov_b32_e32 v115, v121
	v_mov_b32_e32 v95, v124
	v_mov_b32_e32 v97, v125
	v_pk_add_f32 v[102:103], v[112:113], v[114:115]
	v_pk_add_f32 v[94:95], v[96:97], v[94:95]
	s_waitcnt vmcnt(1)
	v_pk_add_f32 v[88:89], v[88:89], 1.0 op_sel_hi:[1,0]
	v_pk_add_f32 v[94:95], v[94:95], v[102:103]
	v_pk_add_f32 v[86:87], v[86:87], 1.0 op_sel_hi:[1,0]
	v_add_f32_e32 v77, v94, v95
	ds_bpermute_b32 v94, v62, v77
	s_waitcnt lgkmcnt(0)
	v_add_f32_e32 v77, v77, v94
	ds_bpermute_b32 v94, v63, v77
	s_waitcnt lgkmcnt(0)
	v_add_f32_e32 v77, v77, v94
	ds_bpermute_b32 v94, v64, v77
	s_waitcnt lgkmcnt(0)
	v_add_f32_e32 v77, v77, v94
	ds_bpermute_b32 v94, v65, v77
	s_waitcnt lgkmcnt(0)
	v_add_f32_e32 v77, v77, v94
	ds_bpermute_b32 v94, v66, v77
	s_waitcnt lgkmcnt(0)
	v_add_f32_e32 v77, v77, v94
	ds_bpermute_b32 v94, v67, v77
	s_waitcnt lgkmcnt(0)
	v_add_f32_e32 v77, v77, v94
	v_fmamk_f32 v77, v77, 0x3a000000, v68
	v_rsq_f32_e32 v94, v77
	s_nop 0
	v_pk_mul_f32 v[80:81], v[80:81], v[94:95] op_sel_hi:[1,0]
	v_pk_mul_f32 v[78:79], v[78:79], v[94:95] op_sel_hi:[1,0]
	v_pk_mul_f32 v[80:81], v[4:5], v[80:81]
	v_pk_mul_f32 v[78:79], v[2:3], v[78:79]
	s_waitcnt vmcnt(0)
	v_pk_fma_f32 v[80:81], v[88:89], v[80:81], v[92:93]
	v_pk_fma_f32 v[78:79], v[86:87], v[78:79], v[90:91]
	v_pk_mul_f32 v[84:85], v[84:85], v[94:95] op_sel_hi:[1,0]
	v_cvt_pk_bf16_f32 v78, v78, v79
	v_cvt_pk_bf16_f32 v79, v80, v81
	global_store_dwordx2 v[60:61], v[78:79], off
	global_load_dwordx4 v[78:81], v70, s[12:13]
	s_nop 0
	global_load_dwordx4 v[86:89], v69, s[10:11] offset:1024
	v_pk_mul_f32 v[82:83], v[82:83], v[94:95] op_sel_hi:[1,0]
	v_pk_mul_f32 v[84:85], v[8:9], v[84:85]
	v_pk_mul_f32 v[82:83], v[6:7], v[82:83]
	v_pk_mul_f32 v[48:49], v[48:49], v[94:95] op_sel_hi:[1,0]
	v_pk_mul_f32 v[46:47], v[46:47], v[94:95] op_sel_hi:[1,0]
	v_pk_mul_f32 v[48:49], v[12:13], v[48:49]
	v_pk_mul_f32 v[46:47], v[10:11], v[46:47]
	v_pk_mul_f32 v[56:57], v[56:57], v[94:95] op_sel_hi:[1,0]
	v_pk_mul_f32 v[54:55], v[54:55], v[94:95] op_sel_hi:[1,0]
	v_pk_mul_f32 v[56:57], v[16:17], v[56:57]
	v_pk_mul_f32 v[54:55], v[14:15], v[54:55]
	v_pk_mul_f32 v[52:53], v[52:53], v[94:95] op_sel_hi:[1,0]
	v_pk_mul_f32 v[50:51], v[50:51], v[94:95] op_sel_hi:[1,0]
	v_pk_mul_f32 v[52:53], v[20:21], v[52:53]
	v_pk_mul_f32 v[50:51], v[18:19], v[50:51]
	v_pk_mul_f32 v[40:41], v[40:41], v[94:95] op_sel_hi:[1,0]
	v_pk_mul_f32 v[38:39], v[38:39], v[94:95] op_sel_hi:[1,0]
	v_pk_mul_f32 v[40:41], v[24:25], v[40:41]
	v_pk_mul_f32 v[38:39], v[22:23], v[38:39]
	v_pk_mul_f32 v[44:45], v[44:45], v[94:95] op_sel_hi:[1,0]
	v_pk_mul_f32 v[42:43], v[42:43], v[94:95] op_sel_hi:[1,0]
	v_pk_mul_f32 v[44:45], v[28:29], v[44:45]
	v_pk_mul_f32 v[42:43], v[26:27], v[42:43]
	v_pk_mul_f32 v[36:37], v[36:37], v[94:95] op_sel_hi:[1,0]
	v_pk_mul_f32 v[34:35], v[34:35], v[94:95] op_sel_hi:[1,0]
	v_pk_mul_f32 v[36:37], v[32:33], v[36:37]
	v_pk_mul_f32 v[34:35], v[30:31], v[34:35]
	s_waitcnt vmcnt(1)
	v_pk_add_f32 v[80:81], v[80:81], 1.0 op_sel_hi:[1,0]
	v_pk_add_f32 v[78:79], v[78:79], 1.0 op_sel_hi:[1,0]
	s_waitcnt vmcnt(0)
	v_pk_fma_f32 v[80:81], v[80:81], v[84:85], v[88:89]
	v_pk_fma_f32 v[78:79], v[78:79], v[82:83], v[86:87]
	s_nop 0
	v_cvt_pk_bf16_f32 v78, v78, v79
	v_cvt_pk_bf16_f32 v79, v80, v81
	global_store_dwordx2 v[60:61], v[78:79], off offset:512
	global_load_dwordx4 v[78:81], v71, s[12:13]
	s_nop 0
	global_load_dwordx4 v[82:85], v69, s[10:11] offset:2048
	s_waitcnt vmcnt(1)
	v_pk_add_f32 v[80:81], v[80:81], 1.0 op_sel_hi:[1,0]
	v_pk_add_f32 v[78:79], v[78:79], 1.0 op_sel_hi:[1,0]
	s_waitcnt vmcnt(0)
	v_pk_fma_f32 v[48:49], v[80:81], v[48:49], v[84:85]
	v_pk_fma_f32 v[46:47], v[78:79], v[46:47], v[82:83]
	s_nop 0
	v_cvt_pk_bf16_f32 v46, v46, v47
	v_cvt_pk_bf16_f32 v47, v48, v49
	global_store_dwordx2 v[60:61], v[46:47], off offset:1024
	global_load_dwordx4 v[46:49], v72, s[12:13]
	s_nop 0
	global_load_dwordx4 v[78:81], v69, s[10:11] offset:3072
	s_waitcnt vmcnt(1)
	v_pk_add_f32 v[48:49], v[48:49], 1.0 op_sel_hi:[1,0]
	v_pk_add_f32 v[46:47], v[46:47], 1.0 op_sel_hi:[1,0]
	s_waitcnt vmcnt(0)
	v_pk_fma_f32 v[48:49], v[48:49], v[56:57], v[80:81]
	v_pk_fma_f32 v[46:47], v[46:47], v[54:55], v[78:79]
	s_nop 0
	v_cvt_pk_bf16_f32 v46, v46, v47
	v_cvt_pk_bf16_f32 v47, v48, v49
	global_store_dwordx2 v[60:61], v[46:47], off offset:1536
	global_load_dwordx4 v[46:49], v73, s[12:13]
	s_nop 0
	global_load_dwordx4 v[54:57], v73, s[10:11]
	s_waitcnt vmcnt(1)
	v_pk_add_f32 v[48:49], v[48:49], 1.0 op_sel_hi:[1,0]
	v_pk_add_f32 v[46:47], v[46:47], 1.0 op_sel_hi:[1,0]
	s_waitcnt vmcnt(0)
	v_pk_fma_f32 v[48:49], v[52:53], v[48:49], v[56:57]
	v_pk_fma_f32 v[46:47], v[50:51], v[46:47], v[54:55]
	s_nop 0
	v_cvt_pk_bf16_f32 v46, v46, v47
	v_cvt_pk_bf16_f32 v47, v48, v49
	global_store_dwordx2 v[60:61], v[46:47], off offset:2048
	global_load_dwordx4 v[46:49], v74, s[12:13]
	s_nop 0
	global_load_dwordx4 v[50:53], v74, s[10:11]
	s_waitcnt vmcnt(1)
	v_pk_add_f32 v[48:49], v[48:49], 1.0 op_sel_hi:[1,0]
	v_pk_add_f32 v[46:47], v[46:47], 1.0 op_sel_hi:[1,0]
	s_waitcnt vmcnt(0)
	v_pk_fma_f32 v[40:41], v[40:41], v[48:49], v[52:53]
	v_pk_fma_f32 v[38:39], v[38:39], v[46:47], v[50:51]
	s_nop 0
	v_cvt_pk_bf16_f32 v38, v38, v39
	v_cvt_pk_bf16_f32 v39, v40, v41
	global_store_dwordx2 v[60:61], v[38:39], off offset:2560
	global_load_dwordx4 v[38:41], v75, s[12:13]
	s_nop 0
	global_load_dwordx4 v[46:49], v75, s[10:11]
	s_waitcnt vmcnt(1)
	v_pk_add_f32 v[40:41], v[40:41], 1.0 op_sel_hi:[1,0]
	v_pk_add_f32 v[38:39], v[38:39], 1.0 op_sel_hi:[1,0]
	s_waitcnt vmcnt(0)
	v_pk_fma_f32 v[40:41], v[44:45], v[40:41], v[48:49]
	v_pk_fma_f32 v[38:39], v[42:43], v[38:39], v[46:47]
	s_nop 0
	v_cvt_pk_bf16_f32 v38, v38, v39
	v_cvt_pk_bf16_f32 v39, v40, v41
	global_store_dwordx2 v[60:61], v[38:39], off offset:3072
	global_load_dwordx4 v[38:41], v76, s[12:13]
	s_nop 0
	global_load_dwordx4 v[42:45], v76, s[10:11]
	s_waitcnt vmcnt(1)
	v_pk_add_f32 v[40:41], v[40:41], 1.0 op_sel_hi:[1,0]
	v_pk_add_f32 v[38:39], v[38:39], 1.0 op_sel_hi:[1,0]
	s_waitcnt vmcnt(0)
	v_pk_fma_f32 v[36:37], v[36:37], v[40:41], v[44:45]
	v_pk_fma_f32 v[34:35], v[34:35], v[38:39], v[42:43]
	s_nop 0
	v_cvt_pk_bf16_f32 v34, v34, v35
	v_cvt_pk_bf16_f32 v35, v36, v37
	global_store_dwordx2 v[60:61], v[34:35], off offset:3584
	v_lshl_add_u64 v[60:61], v[60:61], 0, s[6:7]
	s_cbranch_scc1 .LBB0_196

.LBB0_378:
	s_ashr_i32 s18, s62, 4
	v_lshl_or_b32 v146, s63, 8, v170
	s_mul_hi_i32 s19, s18, 0x12000
	s_mul_i32 s18, s18, 0x12000
	s_add_u32 s18, s45, s18
	v_ashrrev_i32_e32 v147, 31, v146
	v_lshl_add_u32 v166, s62, 8, v168
	s_addc_u32 s19, s54, s19
	v_lshlrev_b64 v[156:157], 2, v[146:147]
	v_ashrrev_i32_e32 v167, 31, v166
	v_lshl_add_u64 v[158:159], s[18:19], 0, v[156:157]
	v_lshl_add_u64 v[164:165], s[8:9], 0, v[156:157]
	v_lshlrev_b64 v[156:157], 13, v[166:167]
	v_lshl_add_u64 v[156:157], v[164:165], 0, v[156:157]
	global_load_dwordx4 v[148:151], v[158:159], off offset:16
	global_load_dwordx4 v[152:155], v[158:159], off
	global_load_dwordx4 v[174:177], v[158:159], off offset:528
	global_load_dwordx4 v[178:181], v[158:159], off offset:512
	global_load_dwordx4 v[182:185], v[156:157], off nt
	global_load_dwordx4 v[186:189], v[156:157], off offset:16 nt
	global_load_dwordx4 v[190:193], v[156:157], off offset:528 nt
	global_load_dwordx4 v[194:197], v[156:157], off offset:512 nt
	v_or_b32_e32 v156, 16, v166
	v_ashrrev_i32_e32 v157, 31, v156
	v_lshlrev_b64 v[158:159], 13, v[156:157]
	v_lshl_add_u64 v[158:159], v[164:165], 0, v[158:159]
	global_load_dwordx4 v[198:201], v[158:159], off nt
	global_load_dwordx4 v[202:205], v[158:159], off offset:16 nt
	global_load_dwordx4 v[206:209], v[158:159], off offset:512 nt
	global_load_dwordx4 v[210:213], v[158:159], off offset:528 nt
	v_or_b32_e32 v246, 32, v166
	v_ashrrev_i32_e32 v247, 31, v246
	v_lshlrev_b64 v[158:159], 13, v[246:247]
	v_lshl_add_u64 v[158:159], v[164:165], 0, v[158:159]
	v_or_b32_e32 v248, 48, v166
	global_load_dwordx4 v[214:217], v[158:159], off nt
	global_load_dwordx4 v[218:221], v[158:159], off offset:16 nt
	global_load_dwordx4 v[222:225], v[158:159], off offset:512 nt
	global_load_dwordx4 v[226:229], v[158:159], off offset:528 nt
	v_ashrrev_i32_e32 v249, 31, v248
	v_lshlrev_b64 v[158:159], 13, v[248:249]
	v_lshl_add_u64 v[158:159], v[164:165], 0, v[158:159]
	global_load_dwordx4 v[230:233], v[158:159], off nt
	global_load_dwordx4 v[234:237], v[158:159], off offset:16 nt
	global_load_dwordx4 v[238:241], v[158:159], off offset:528 nt
	global_load_dwordx4 v[242:245], v[158:159], off offset:512 nt
	v_lshlrev_b64 v[160:161], 12, v[166:167]
	v_lshlrev_b64 v[156:157], 12, v[156:157]
	v_lshlrev_b64 v[146:147], 1, v[146:147]
	v_lshl_add_u64 v[160:161], s[12:13], 0, v[160:161]
	v_lshl_add_u64 v[156:157], s[12:13], 0, v[156:157]
	v_lshl_add_u64 v[250:251], v[160:161], 0, v[146:147]
	v_lshl_add_u64 v[252:253], v[156:157], 0, v[146:147]
	s_and_b64 vcc, exec, s[0:1]
	s_mov_b64 s[0:1], -1
	s_waitcnt vmcnt(0)
	v_pk_mul_f32 v[156:157], v[150:151], 0.5 op_sel_hi:[1,0]
	v_pk_mul_f32 v[160:161], v[154:155], 0.5 op_sel_hi:[1,0]
	v_pk_mul_f32 v[162:163], v[152:153], 0.5 op_sel_hi:[1,0]
	v_pk_mul_f32 v[158:159], v[148:149], 0.5 op_sel_hi:[1,0]
	v_pk_mul_f32 v[152:153], v[180:181], 0.5 op_sel_hi:[1,0]
	v_pk_mul_f32 v[154:155], v[178:179], 0.5 op_sel_hi:[1,0]
	v_pk_mul_f32 v[148:149], v[176:177], 0.5 op_sel_hi:[1,0]
	v_pk_mul_f32 v[150:151], v[174:175], 0.5 op_sel_hi:[1,0]
	v_pk_fma_f32 v[128:129], v[128:129], v[160:161], v[184:185]
	v_pk_fma_f32 v[126:127], v[126:127], v[162:163], v[182:183]
	v_pk_fma_f32 v[124:125], v[124:125], v[156:157], v[188:189]
	v_pk_fma_f32 v[122:123], v[122:123], v[158:159], v[186:187]
	v_pk_fma_f32 v[112:113], v[112:113], v[152:153], v[196:197]
	v_pk_fma_f32 v[110:111], v[110:111], v[154:155], v[194:195]
	v_pk_fma_f32 v[174:175], v[108:109], v[148:149], v[192:193]
	v_pk_fma_f32 v[176:177], v[106:107], v[150:151], v[190:191]
	v_pk_fma_f32 v[120:121], v[120:121], v[160:161], v[200:201]
	v_pk_fma_f32 v[118:119], v[118:119], v[162:163], v[198:199]
	v_pk_fma_f32 v[178:179], v[116:117], v[156:157], v[204:205]
	v_pk_fma_f32 v[116:117], v[114:115], v[158:159], v[202:203]
	v_cvt_pk_f16_f32 v106, v126, v127
	v_cvt_pk_f16_f32 v107, v128, v129
	v_cvt_pk_f16_f32 v108, v122, v123
	v_cvt_pk_f16_f32 v109, v124, v125
	v_pk_fma_f32 v[100:101], v[100:101], v[152:153], v[208:209]
	v_cvt_pk_f16_f32 v110, v110, v111
	v_cvt_pk_f16_f32 v111, v112, v113
	v_cvt_pk_f16_f32 v112, v176, v177
	v_cvt_pk_f16_f32 v113, v174, v175
	v_cvt_pk_f16_f32 v114, v118, v119
	v_cvt_pk_f16_f32 v115, v120, v121
	v_cvt_pk_f16_f32 v116, v116, v117
	v_cvt_pk_f16_f32 v117, v178, v179
	global_store_dwordx4 v[250:251], v[106:109], off sc1
	global_store_dwordx4 v[250:251], v[110:113], off offset:256 sc1
	global_store_dwordx4 v[252:253], v[114:117], off sc1
	v_pk_fma_f32 v[98:99], v[98:99], v[154:155], v[206:207]
	v_pk_fma_f32 v[106:107], v[92:93], v[148:149], v[212:213]
	v_pk_fma_f32 v[92:93], v[90:91], v[150:151], v[210:211]
	v_cvt_pk_f16_f32 v90, v98, v99
	v_cvt_pk_f16_f32 v91, v100, v101
	v_cvt_pk_f16_f32 v92, v92, v93
	v_cvt_pk_f16_f32 v93, v106, v107
	global_store_dwordx4 v[252:253], v[90:93], off offset:256 sc1
	v_lshlrev_b64 v[98:99], 12, v[246:247]
	v_pk_fma_f32 v[94:95], v[94:95], v[158:159], v[218:219]
	v_pk_fma_f32 v[92:93], v[104:105], v[160:161], v[216:217]
	v_pk_fma_f32 v[90:91], v[102:103], v[162:163], v[214:215]
	v_pk_fma_f32 v[96:97], v[96:97], v[156:157], v[220:221]
	v_cvt_pk_f16_f32 v90, v90, v91
	v_cvt_pk_f16_f32 v91, v92, v93
	v_cvt_pk_f16_f32 v92, v94, v95
	v_lshl_add_u64 v[94:95], s[12:13], 0, v[98:99]
	v_cvt_pk_f16_f32 v93, v96, v97
	v_lshl_add_u64 v[94:95], v[94:95], 0, v[146:147]
	global_store_dwordx4 v[94:95], v[90:93], off sc1
	v_pk_fma_f32 v[84:85], v[84:85], v[152:153], v[224:225]
	v_pk_fma_f32 v[82:83], v[82:83], v[154:155], v[222:223]
	v_pk_fma_f32 v[90:91], v[76:77], v[148:149], v[228:229]
	v_pk_fma_f32 v[76:77], v[74:75], v[150:151], v[226:227]
	v_cvt_pk_f16_f32 v74, v82, v83
	v_cvt_pk_f16_f32 v75, v84, v85
	v_cvt_pk_f16_f32 v76, v76, v77
	v_cvt_pk_f16_f32 v77, v90, v91
	global_store_dwordx4 v[94:95], v[74:77], off offset:256 sc1
	v_lshlrev_b64 v[82:83], 12, v[248:249]
	v_pk_fma_f32 v[78:79], v[78:79], v[158:159], v[234:235]
	v_pk_fma_f32 v[76:77], v[88:89], v[160:161], v[232:233]
	v_pk_fma_f32 v[74:75], v[86:87], v[162:163], v[230:231]
	v_pk_fma_f32 v[80:81], v[80:81], v[156:157], v[236:237]
	v_cvt_pk_f16_f32 v74, v74, v75
	v_cvt_pk_f16_f32 v75, v76, v77
	v_cvt_pk_f16_f32 v76, v78, v79
	v_lshl_add_u64 v[78:79], s[12:13], 0, v[82:83]
	v_cvt_pk_f16_f32 v77, v80, v81
	v_lshl_add_u64 v[78:79], v[78:79], 0, v[146:147]
	global_store_dwordx4 v[78:79], v[74:77], off sc1
	v_pk_fma_f32 v[72:73], v[72:73], v[152:153], v[244:245]
	v_pk_fma_f32 v[70:71], v[70:71], v[154:155], v[242:243]
	v_pk_fma_f32 v[74:75], v[68:69], v[148:149], v[240:241]
	v_pk_fma_f32 v[68:69], v[66:67], v[150:151], v[238:239]
	v_add_u32_e32 v174, 0x80, v166
	v_cvt_pk_f16_f32 v66, v70, v71
	v_cvt_pk_f16_f32 v67, v72, v73
	v_cvt_pk_f16_f32 v68, v68, v69
	v_cvt_pk_f16_f32 v69, v74, v75
	v_ashrrev_i32_e32 v175, 31, v174
	global_store_dwordx4 v[78:79], v[66:69], off offset:256 sc1
	v_add_u32_e32 v176, 0x90, v166
	v_ashrrev_i32_e32 v177, 31, v176
	v_lshlrev_b64 v[66:67], 13, v[174:175]
	v_lshl_add_u64 v[78:79], v[164:165], 0, v[66:67]
	global_load_dwordx4 v[66:69], v[78:79], off nt
	global_load_dwordx4 v[70:73], v[78:79], off offset:16 nt
	global_load_dwordx4 v[74:77], v[78:79], off offset:512 nt
	s_nop 0
	global_load_dwordx4 v[78:81], v[78:79], off offset:528 nt
	v_lshlrev_b64 v[82:83], 13, v[176:177]
	v_lshl_add_u64 v[94:95], v[164:165], 0, v[82:83]
	global_load_dwordx4 v[82:85], v[94:95], off nt
	global_load_dwordx4 v[86:89], v[94:95], off offset:16 nt
	global_load_dwordx4 v[90:93], v[94:95], off offset:512 nt
	s_nop 0
	global_load_dwordx4 v[94:97], v[94:95], off offset:528 nt
	v_add_u32_e32 v178, 0xa0, v166
	v_ashrrev_i32_e32 v179, 31, v178
	v_lshlrev_b64 v[98:99], 13, v[178:179]
	v_lshl_add_u64 v[110:111], v[164:165], 0, v[98:99]
	global_load_dwordx4 v[98:101], v[110:111], off nt
	global_load_dwordx4 v[102:105], v[110:111], off offset:16 nt
	global_load_dwordx4 v[106:109], v[110:111], off offset:512 nt
	s_nop 0
	global_load_dwordx4 v[110:113], v[110:111], off offset:528 nt
	v_add_u32_e32 v166, 0xb0, v166
	v_ashrrev_i32_e32 v167, 31, v166
	v_lshlrev_b64 v[114:115], 13, v[166:167]
	v_lshl_add_u64 v[126:127], v[164:165], 0, v[114:115]
	global_load_dwordx4 v[114:117], v[126:127], off nt
	global_load_dwordx4 v[118:121], v[126:127], off offset:16 nt
	global_load_dwordx4 v[122:125], v[126:127], off offset:512 nt
	s_nop 0
	global_load_dwordx4 v[126:129], v[126:127], off offset:528 nt
	v_lshlrev_b64 v[164:165], 12, v[174:175]
	s_waitcnt vmcnt(15)
	v_pk_fma_f32 v[62:63], v[62:63], v[162:163], v[66:67]
	v_pk_fma_f32 v[64:65], v[64:65], v[160:161], v[68:69]
	s_waitcnt vmcnt(14)
	v_pk_fma_f32 v[66:67], v[60:61], v[156:157], v[72:73]
	v_pk_fma_f32 v[60:61], v[58:59], v[158:159], v[70:71]
	v_cvt_pk_f16_f32 v58, v62, v63
	v_lshl_add_u64 v[62:63], s[12:13], 0, v[164:165]
	v_cvt_pk_f16_f32 v59, v64, v65
	v_cvt_pk_f16_f32 v60, v60, v61
	v_cvt_pk_f16_f32 v61, v66, v67
	v_lshl_add_u64 v[62:63], v[62:63], 0, v[146:147]
	global_store_dwordx4 v[62:63], v[58:61], off sc1
	s_waitcnt vmcnt(14)
	v_pk_fma_f32 v[52:53], v[52:53], v[152:153], v[76:77]
	v_pk_fma_f32 v[50:51], v[50:51], v[154:155], v[74:75]
	s_waitcnt vmcnt(13)
	v_pk_fma_f32 v[58:59], v[44:45], v[148:149], v[80:81]
	v_pk_fma_f32 v[44:45], v[42:43], v[150:151], v[78:79]
	v_cvt_pk_f16_f32 v42, v50, v51
	v_cvt_pk_f16_f32 v43, v52, v53
	v_cvt_pk_f16_f32 v44, v44, v45
	v_cvt_pk_f16_f32 v45, v58, v59
	global_store_dwordx4 v[62:63], v[42:45], off offset:256 sc1
	v_lshlrev_b64 v[50:51], 12, v[176:177]
	s_waitcnt vmcnt(12)
	v_pk_fma_f32 v[46:47], v[46:47], v[158:159], v[86:87]
	v_pk_fma_f32 v[44:45], v[56:57], v[160:161], v[84:85]
	v_pk_fma_f32 v[42:43], v[54:55], v[162:163], v[82:83]
	v_pk_fma_f32 v[48:49], v[48:49], v[156:157], v[88:89]
	v_cvt_pk_f16_f32 v42, v42, v43
	v_cvt_pk_f16_f32 v43, v44, v45
	v_cvt_pk_f16_f32 v44, v46, v47
	v_lshl_add_u64 v[46:47], s[12:13], 0, v[50:51]
	v_cvt_pk_f16_f32 v45, v48, v49
	v_lshl_add_u64 v[46:47], v[46:47], 0, v[146:147]
	global_store_dwordx4 v[46:47], v[42:45], off sc1
	s_waitcnt vmcnt(12)
	v_pk_fma_f32 v[36:37], v[36:37], v[152:153], v[92:93]
	v_pk_fma_f32 v[34:35], v[34:35], v[154:155], v[90:91]
	s_waitcnt vmcnt(11)
	v_pk_fma_f32 v[42:43], v[28:29], v[148:149], v[96:97]
	v_pk_fma_f32 v[28:29], v[26:27], v[150:151], v[94:95]
	v_cvt_pk_f16_f32 v26, v34, v35
	v_cvt_pk_f16_f32 v27, v36, v37
	v_cvt_pk_f16_f32 v28, v28, v29
	v_cvt_pk_f16_f32 v29, v42, v43
	global_store_dwordx4 v[46:47], v[26:29], off offset:256 sc1
	v_lshlrev_b64 v[34:35], 12, v[178:179]
	s_waitcnt vmcnt(10)
	v_pk_fma_f32 v[30:31], v[30:31], v[158:159], v[102:103]
	v_pk_fma_f32 v[28:29], v[40:41], v[160:161], v[100:101]
	v_pk_fma_f32 v[26:27], v[38:39], v[162:163], v[98:99]
	v_pk_fma_f32 v[32:33], v[32:33], v[156:157], v[104:105]
	v_cvt_pk_f16_f32 v26, v26, v27
	v_cvt_pk_f16_f32 v27, v28, v29
	v_cvt_pk_f16_f32 v28, v30, v31
	v_lshl_add_u64 v[30:31], s[12:13], 0, v[34:35]
	v_cvt_pk_f16_f32 v29, v32, v33
	v_lshl_add_u64 v[30:31], v[30:31], 0, v[146:147]
	global_store_dwordx4 v[30:31], v[26:29], off sc1
	s_waitcnt vmcnt(10)
	v_pk_fma_f32 v[20:21], v[20:21], v[152:153], v[108:109]
	v_pk_fma_f32 v[18:19], v[18:19], v[154:155], v[106:107]
	s_waitcnt vmcnt(9)
	v_pk_fma_f32 v[26:27], v[12:13], v[148:149], v[112:113]
	v_pk_fma_f32 v[12:13], v[10:11], v[150:151], v[110:111]
	v_cvt_pk_f16_f32 v10, v18, v19
	v_cvt_pk_f16_f32 v11, v20, v21
	v_cvt_pk_f16_f32 v12, v12, v13
	v_cvt_pk_f16_f32 v13, v26, v27
	global_store_dwordx4 v[30:31], v[10:13], off offset:256 sc1
	v_lshlrev_b64 v[18:19], 12, v[166:167]
	s_waitcnt vmcnt(8)
	v_pk_fma_f32 v[14:15], v[14:15], v[158:159], v[118:119]
	v_pk_fma_f32 v[12:13], v[24:25], v[160:161], v[116:117]
	v_pk_fma_f32 v[10:11], v[22:23], v[162:163], v[114:115]
	v_pk_fma_f32 v[16:17], v[16:17], v[156:157], v[120:121]
	v_cvt_pk_f16_f32 v10, v10, v11
	v_cvt_pk_f16_f32 v11, v12, v13
	v_cvt_pk_f16_f32 v12, v14, v15
	v_lshl_add_u64 v[14:15], s[12:13], 0, v[18:19]
	v_cvt_pk_f16_f32 v13, v16, v17
	v_lshl_add_u64 v[14:15], v[14:15], 0, v[146:147]
	global_store_dwordx4 v[14:15], v[10:13], off sc1
	s_waitcnt vmcnt(8)
	v_pk_fma_f32 v[8:9], v[8:9], v[152:153], v[124:125]
	v_pk_fma_f32 v[6:7], v[6:7], v[154:155], v[122:123]
	s_waitcnt vmcnt(7)
	v_pk_fma_f32 v[10:11], v[4:5], v[148:149], v[128:129]
	v_pk_fma_f32 v[4:5], v[2:3], v[150:151], v[126:127]
	v_cvt_pk_f16_f32 v2, v6, v7
	v_cvt_pk_f16_f32 v3, v8, v9
	v_cvt_pk_f16_f32 v4, v4, v5
	v_cvt_pk_f16_f32 v5, v10, v11
	global_store_dwordx4 v[14:15], v[2:5], off offset:256 sc1
	s_cbranch_vccnz .LBB0_363
	s_andn2_b64 vcc, exec, s[10:11]
	s_cbranch_vccnz .LBB0_362
	s_barrier
	s_branch .LBB0_362

.LBB0_382:
	v_readlane_b32 s0, v254, 0
	v_readlane_b32 s1, v254, 1
	s_cmp_gt_i32 s1, 4
	s_cselect_b64 s[0:1], -1, 0
	s_and_b64 s[4:5], s[6:7], s[0:1]
	s_andn2_b64 vcc, exec, s[4:5]
	s_cbranch_vccnz .LBB0_436
	s_waitcnt vmcnt(0)
	s_waitcnt vmcnt(0) lgkmcnt(0)
	s_barrier
	s_mov_b64 s[4:5], exec
	v_readlane_b32 s6, v254, 7
	v_readlane_b32 s7, v254, 8
	s_and_b64 s[6:7], s[4:5], s[6:7]
	s_mov_b64 exec, s[6:7]
	s_cbranch_execz .Lmy_cv3_entry
	s_cmpk_lg_i32 s3, 0x100
	s_cbranch_scc1 .Lmy_gb3_orig
	s_and_b32 s6, s2, 7
	s_lshl_b32 s6, s6, 6
	s_add_u32 s6, s6, 0x33a00
	v_mov_b32_e32 v2, s6
	v_mov_b32_e32 v3, 1
	global_atomic_add v2, v3, s[50:51]
	s_movk_i32 s7, 0x4000
.Lmy_gb3_spin:
	global_load_dword v4, v2, s[50:51] sc1
	s_waitcnt vmcnt(0)
	v_cmp_gt_u32_e32 vcc, 32, v4
	s_cbranch_vccz .Lmy_gb3_go
	s_sleep 1
	s_sub_u32 s7, s7, 1
	s_cmp_lg_u32 s7, 0
	s_cbranch_scc1 .Lmy_gb3_spin

.Lmy_gb3_orig:
	s_add_i32 s6, 0, 0x23fc0
	v_mov_b32_e32 v2, s6
	s_waitcnt vmcnt(0) expcnt(0) lgkmcnt(0)
	ds_read_b32 v4, v2
	s_add_i32 s6, 0, 0x23fc4
	v_mov_b32_e32 v2, s6
	ds_read_b32 v2, v2
	s_waitcnt lgkmcnt(1)
	v_cmp_ne_u32_e32 vcc, 0, v4
	s_cbranch_vccnz .LBB0_399
	v_readlane_b32 s6, v254, 2
	v_readlane_b32 s7, v254, 3
	s_load_dwordx2 s[10:11], s[6:7], 0x4
	s_add_u32 s6, s50, 0x28200
	s_addc_u32 s7, s51, 0
	s_add_u32 s8, s50, 0x28400
	s_addc_u32 s9, s51, 0
	s_waitcnt lgkmcnt(0)
	s_mul_i32 s28, s10, s3
	s_add_u32 s10, s50, 0x28500
	s_mul_i32 s28, s28, s11
	s_addc_u32 s11, s51, 0
	s_add_u32 s12, s50, 0x28600
	s_addc_u32 s13, s51, 0
	s_add_u32 s14, s50, 0x28700
	s_addc_u32 s15, s51, 0
	s_add_u32 s16, s50, 0x28800
	s_addc_u32 s17, s51, 0
	s_add_u32 s18, s50, 0x28900
	s_addc_u32 s19, s51, 0
	s_add_u32 s20, s50, 0x28a00
	s_addc_u32 s21, s51, 0
	s_add_u32 s22, s50, 0x28b00
	s_addc_u32 s23, s51, 0
	s_add_u32 s24, s50, 0x28c00
	s_addc_u32 s25, s51, 0
	s_add_u32 s26, s50, 0x28d00
	s_addc_u32 s27, s51, 0
	s_add_u32 s42, s50, 0x28e00
	s_addc_u32 s43, s51, 0
	s_add_u32 s44, s50, 0x28f00
	s_addc_u32 s45, s51, 0
	s_add_u32 s54, s50, 0x29000
	s_addc_u32 s55, s51, 0
	s_add_u32 s56, s50, 0x29100
	s_addc_u32 s57, s51, 0
	s_add_u32 s58, s50, 0x29200
	s_addc_u32 s59, s51, 0
	s_add_u32 s60, s50, 0x29300
	s_addc_u32 s61, s51, 0
	s_mov_b32 s29, 1
	v_mov_b32_e32 v18, 0
	s_branch .LBB0_387

.LBB0_436:
	v_readlane_b32 s4, v254, 0
	v_readlane_b32 s5, v254, 1
	s_cmp_lt_i32 s4, 5
	s_cselect_b64 s[4:5], -1, 0
	s_and_b64 s[4:5], s[4:5], s[0:1]
	s_andn2_b64 vcc, exec, s[4:5]
	s_cbranch_vccnz .LBB0_440
	s_cmpk_gt_i32 s70, 0x1fff
	s_cbranch_scc1 .LBB0_440
	s_mov_b32 s98, s70
	s_movk_i32 s100, 0x2000
	s_mov_b32 s101, s72
	s_cmpk_lg_i32 s3, 0x100
	s_cbranch_scc1 .Lmy_gr4
	s_and_b32 s98, s2, 7
	s_lshl_b32 s98, s98, 10
	s_add_i32 s100, s98, 0x400
	s_lshr_b32 s99, s2, 3
	s_lshl_b32 s99, s99, 3
	s_add_i32 s98, s98, s99
	v_readlane_b32 s99, v254, 10
	s_add_i32 s98, s98, s99
	s_movk_i32 s101, 0x100
.Lmy_gr4:
	s_mov_b32 s99, 0
	v_lshlrev_b32_e32 v36, 3, v1
	v_lshlrev_b32_e32 v18, 5, v1
	s_waitcnt lgkmcnt(0)
	global_load_dwordx4 v[2:5], v18, s[52:53] offset:16
	global_load_dwordx4 v[6:9], v18, s[52:53]
	global_load_dwordx4 v[10:13], v18, s[52:53] offset:2064
	global_load_dwordx4 v[14:17], v18, s[52:53] offset:2048
	v_or_b32_e32 v38, 0x400, v36
	v_or_b32_e32 v40, 0x600, v36
	v_lshlrev_b32_e32 v26, 2, v38
	v_lshlrev_b32_e32 v34, 2, v40
	global_load_dwordx4 v[18:21], v26, s[52:53] offset:16
	global_load_dwordx4 v[22:25], v26, s[52:53]
	s_nop 0
	global_load_dwordx4 v[26:29], v34, s[52:53] offset:16
	global_load_dwordx4 v[30:33], v34, s[52:53]
	v_mbcnt_lo_u32_b32 v34, -1, 0
	v_mbcnt_hi_u32_b32 v34, -1, v34
	v_and_b32_e32 v35, 64, v34
	v_add_u32_e32 v35, 64, v35
	v_xor_b32_e32 v37, 1, v34
	v_cmp_lt_i32_e32 vcc, v37, v35
	s_ashr_i32 s71, s70, 31
	s_lshl_b64 s[0:1], s[98:99], 12
	v_cndmask_b32_e32 v37, v34, v37, vcc
	v_lshlrev_b32_e32 v44, 2, v37
	v_xor_b32_e32 v37, 2, v34
	v_cmp_lt_i32_e32 vcc, v37, v35
	s_add_u32 s0, s50, s0
	s_addc_u32 s1, s51, s1
	v_cndmask_b32_e32 v37, v34, v37, vcc
	v_lshlrev_b32_e32 v45, 2, v37
	v_xor_b32_e32 v37, 4, v34
	v_cmp_lt_i32_e32 vcc, v37, v35
	v_or_b32_e32 v42, 0x200, v36
	s_ashr_i32 s73, s72, 31
	v_cndmask_b32_e32 v37, v34, v37, vcc
	v_lshlrev_b32_e32 v46, 2, v37
	v_xor_b32_e32 v37, 8, v34
	v_cmp_lt_i32_e32 vcc, v37, v35
	v_mov_b32_e32 v50, 0x358637bd
	v_lshlrev_b32_e32 v51, 2, v36
	v_cndmask_b32_e32 v37, v34, v37, vcc
	v_lshlrev_b32_e32 v47, 2, v37
	v_xor_b32_e32 v37, 16, v34
	v_cmp_lt_i32_e32 vcc, v37, v35
	s_mov_b32 s10, 0xee800000
	v_lshlrev_b32_e32 v52, 2, v42
	v_cndmask_b32_e32 v37, v34, v37, vcc
	v_lshlrev_b32_e32 v48, 2, v37
	v_xor_b32_e32 v37, 32, v34
	v_cmp_lt_i32_e32 vcc, v37, v35
	v_mov_b32_e32 v35, 0
	s_mov_b32 s11, 0xee801000
	v_cndmask_b32_e32 v34, v34, v37, vcc
	v_lshlrev_b32_e32 v49, 2, v34
	v_lshlrev_b32_e32 v34, 4, v1
	v_lshl_add_u64 v[34:35], s[0:1], 0, v[34:35]
	s_mov_b64 s[0:1], 0x1c400000
	v_lshl_add_u64 v[34:35], v[34:35], 0, s[0:1]
	s_lshl_b32 s0, s101, 12
	s_mov_b32 s1, 0
	v_lshlrev_b32_e32 v53, 2, v38
	v_lshlrev_b32_e32 v54, 2, v40
	s_mov_b32 s12, s98
.LBB0_439:
	global_load_dwordx4 v[36:39], v[34:35], off nt
	global_load_dwordx4 v[40:43], v[34:35], off offset:1024 nt
	global_load_dwordx4 v[56:59], v[34:35], off offset:2048 nt
	global_load_dwordx4 v[60:63], v[34:35], off offset:3072 nt
	s_ashr_i32 s6, s12, 12
	s_mul_hi_i32 s7, s6, 0x12000
	s_mul_i32 s6, s6, 0x12000
	s_add_u32 s8, s50, s6
	s_addc_u32 s9, s51, s7
	s_add_u32 s6, s8, 0x6000
	s_addc_u32 s7, s9, 0
	s_add_u32 s8, s8, 0x8000
	s_addc_u32 s9, s9, 0
	global_load_dwordx4 v[64:67], v51, s[6:7] offset:16
	global_load_dwordx4 v[68:71], v51, s[6:7]
	global_load_dwordx4 v[72:75], v51, s[8:9] offset:16
	global_load_dwordx4 v[76:79], v51, s[8:9]
	v_add_co_u32_e32 v80, vcc, s10, v34
	s_add_i32 s12, s12, s101
	s_nop 0
	v_addc_co_u32_e32 v81, vcc, -1, v35, vcc
	s_cmp_lt_i32 s12, s100
	s_waitcnt vmcnt(0)
	v_cvt_f32_f16_sdwa v83, v36 dst_sel:DWORD dst_unused:UNUSED_PAD src0_sel:WORD_1
	v_cvt_f32_f16_sdwa v85, v37 dst_sel:DWORD dst_unused:UNUSED_PAD src0_sel:WORD_1
	v_cvt_f32_f16_sdwa v87, v38 dst_sel:DWORD dst_unused:UNUSED_PAD src0_sel:WORD_1
	v_cvt_f32_f16_sdwa v89, v39 dst_sel:DWORD dst_unused:UNUSED_PAD src0_sel:WORD_1
	v_cvt_f32_f16_e32 v82, v36
	v_cvt_f32_f16_e32 v84, v37
	v_cvt_f32_f16_e32 v86, v38
	v_cvt_f32_f16_e32 v88, v39
	v_cvt_f32_f16_sdwa v91, v40 dst_sel:DWORD dst_unused:UNUSED_PAD src0_sel:WORD_1
	v_cvt_f32_f16_sdwa v93, v41 dst_sel:DWORD dst_unused:UNUSED_PAD src0_sel:WORD_1
	v_cvt_f32_f16_e32 v90, v40
	v_cvt_f32_f16_e32 v92, v41
	v_cvt_f32_f16_e32 v94, v42
	v_cvt_f32_f16_e32 v96, v43
	v_cvt_f32_f16_sdwa v95, v42 dst_sel:DWORD dst_unused:UNUSED_PAD src0_sel:WORD_1
	v_cvt_f32_f16_sdwa v97, v43 dst_sel:DWORD dst_unused:UNUSED_PAD src0_sel:WORD_1
	v_cvt_f32_f16_sdwa v99, v56 dst_sel:DWORD dst_unused:UNUSED_PAD src0_sel:WORD_1
	v_cvt_f32_f16_e32 v98, v56
	v_cvt_f32_f16_sdwa v101, v57 dst_sel:DWORD dst_unused:UNUSED_PAD src0_sel:WORD_1
	v_cvt_f32_f16_e32 v100, v57
	v_cvt_f32_f16_sdwa v103, v58 dst_sel:DWORD dst_unused:UNUSED_PAD src0_sel:WORD_1
	v_cvt_f32_f16_e32 v102, v58
	v_cvt_f32_f16_sdwa v105, v59 dst_sel:DWORD dst_unused:UNUSED_PAD src0_sel:WORD_1
	v_cvt_f32_f16_e32 v104, v59
	v_cvt_f32_f16_sdwa v39, v62 dst_sel:DWORD dst_unused:UNUSED_PAD src0_sel:WORD_1
	v_cvt_f32_f16_e32 v38, v62
	v_cvt_f32_f16_sdwa v43, v63 dst_sel:DWORD dst_unused:UNUSED_PAD src0_sel:WORD_1
	v_cvt_f32_f16_e32 v42, v63
	v_mov_b32_e32 v58, v83
	v_mov_b32_e32 v59, v87
	v_mov_b32_e32 v62, v85
	v_mov_b32_e32 v63, v89
	v_cvt_f32_f16_sdwa v37, v60 dst_sel:DWORD dst_unused:UNUSED_PAD src0_sel:WORD_1
	v_cvt_f32_f16_e32 v36, v60
	v_cvt_f32_f16_sdwa v41, v61 dst_sel:DWORD dst_unused:UNUSED_PAD src0_sel:WORD_1
	v_cvt_f32_f16_e32 v40, v61
	v_mov_b32_e32 v56, v82
	v_mov_b32_e32 v57, v86
	v_mov_b32_e32 v60, v84
	v_mov_b32_e32 v61, v88
	v_mov_b32_e32 v108, v91
	v_mov_b32_e32 v109, v93
	v_pk_mul_f32 v[58:59], v[58:59], v[58:59]
	v_pk_mul_f32 v[62:63], v[62:63], v[62:63]
	v_mov_b32_e32 v106, v90
	v_mov_b32_e32 v107, v92
	v_pk_mul_f32 v[108:109], v[108:109], v[108:109]
	v_pk_fma_f32 v[56:57], v[56:57], v[56:57], v[58:59]
	v_pk_fma_f32 v[58:59], v[60:61], v[60:61], v[62:63]
	v_mul_f32_e32 v110, v94, v94
	v_mul_f32_e32 v112, v96, v96
	v_pk_fma_f32 v[60:61], v[106:107], v[106:107], v[108:109]
	v_pk_add_f32 v[56:57], v[56:57], v[58:59]
	v_pk_mul_f32 v[114:115], v[98:99], v[98:99]
	v_pk_mul_f32 v[116:117], v[100:101], v[100:101]
	v_pk_fma_f32 v[110:111], v[94:95], v[94:95], v[110:111] op_sel_hi:[1,1,0]
	v_pk_fma_f32 v[112:113], v[96:97], v[96:97], v[112:113] op_sel_hi:[1,1,0]
	v_pk_add_f32 v[58:59], v[60:61], v[60:61] op_sel_hi:[0,1]
	v_pk_add_f32 v[56:57], v[56:57], v[56:57] op_sel_hi:[0,1]
	v_mov_b32_e32 v120, v103
	v_mov_b32_e32 v121, v105
	v_mov_b32_e32 v110, v114
	v_mov_b32_e32 v112, v115
	v_mov_b32_e32 v58, v117
	v_mov_b32_e32 v56, v116
	v_mov_b32_e32 v118, v102
	v_mov_b32_e32 v119, v104
	v_pk_mul_f32 v[120:121], v[120:121], v[120:121]
	v_pk_add_f32 v[60:61], v[110:111], v[112:113]
	v_pk_add_f32 v[56:57], v[56:57], v[58:59]
	v_mul_f32_e32 v122, v36, v36
	v_mul_f32_e32 v124, v40, v40
	v_pk_fma_f32 v[62:63], v[118:119], v[118:119], v[120:121]
	v_pk_add_f32 v[56:57], v[60:61], v[56:57]
	v_pk_mul_f32 v[126:127], v[38:39], v[38:39]
	v_pk_mul_f32 v[128:129], v[42:43], v[42:43]
	v_pk_fma_f32 v[122:123], v[36:37], v[36:37], v[122:123] op_sel_hi:[1,1,0]
	v_pk_fma_f32 v[124:125], v[40:41], v[40:41], v[124:125] op_sel_hi:[1,1,0]
	v_pk_add_f32 v[62:63], v[62:63], v[62:63] op_sel_hi:[0,1]
	v_pk_add_f32 v[56:57], v[56:57], v[56:57] op_sel_hi:[0,1]
	v_mov_b32_e32 v122, v126
	v_mov_b32_e32 v124, v127
	v_mov_b32_e32 v62, v128
	v_mov_b32_e32 v56, v129
	v_pk_add_f32 v[106:107], v[122:123], v[124:125]
	v_pk_add_f32 v[56:57], v[62:63], v[56:57]
	v_pk_add_f32 v[78:79], v[78:79], 1.0 op_sel_hi:[1,0]
	v_pk_add_f32 v[56:57], v[106:107], v[56:57]
	v_pk_add_f32 v[76:77], v[76:77], 1.0 op_sel_hi:[1,0]
	v_add_f32_e32 v55, v56, v57
	ds_bpermute_b32 v56, v44, v55
	v_pk_add_f32 v[74:75], v[74:75], 1.0 op_sel_hi:[1,0]
	v_pk_add_f32 v[72:73], v[72:73], 1.0 op_sel_hi:[1,0]
	s_waitcnt lgkmcnt(0)
	v_add_f32_e32 v55, v55, v56
	ds_bpermute_b32 v56, v45, v55
	s_waitcnt lgkmcnt(0)
	v_add_f32_e32 v55, v55, v56
	ds_bpermute_b32 v56, v46, v55
	s_waitcnt lgkmcnt(0)
	v_add_f32_e32 v55, v55, v56
	ds_bpermute_b32 v56, v47, v55
	s_waitcnt lgkmcnt(0)
	v_add_f32_e32 v55, v55, v56
	ds_bpermute_b32 v56, v48, v55
	s_waitcnt lgkmcnt(0)
	v_add_f32_e32 v55, v55, v56
	ds_bpermute_b32 v56, v49, v55
	s_waitcnt lgkmcnt(0)
	v_add_f32_e32 v55, v55, v56
	v_fmamk_f32 v55, v55, 0x3a000000, v50
	v_rsq_f32_e32 v106, v55
	s_nop 0
	v_pk_mul_f32 v[56:57], v[84:85], v[106:107] op_sel_hi:[1,0]
	v_pk_mul_f32 v[58:59], v[82:83], v[106:107] op_sel_hi:[1,0]
	v_pk_mul_f32 v[60:61], v[88:89], v[106:107] op_sel_hi:[1,0]
	v_pk_mul_f32 v[62:63], v[86:87], v[106:107] op_sel_hi:[1,0]
	v_pk_mul_f32 v[58:59], v[6:7], v[58:59]
	v_pk_mul_f32 v[56:57], v[8:9], v[56:57]
	v_pk_mul_f32 v[62:63], v[2:3], v[62:63]
	v_pk_mul_f32 v[60:61], v[4:5], v[60:61]
	v_pk_fma_f32 v[70:71], v[78:79], v[56:57], v[70:71]
	v_pk_fma_f32 v[56:57], v[76:77], v[58:59], v[68:69]
	v_pk_fma_f32 v[60:61], v[74:75], v[60:61], v[66:67]
	v_pk_fma_f32 v[58:59], v[72:73], v[62:63], v[64:65]
	v_cvt_pk_bf16_f32 v56, v56, v57
	v_cvt_pk_bf16_f32 v57, v70, v71
	v_cvt_pk_bf16_f32 v58, v58, v59
	v_cvt_pk_bf16_f32 v59, v60, v61
	global_store_dwordx4 v[80:81], v[56:59], off sc1
	global_load_dwordx4 v[56:59], v52, s[8:9]
	s_nop 0
	global_load_dwordx4 v[60:63], v52, s[8:9] offset:16
	global_load_dwordx4 v[64:67], v52, s[6:7]
	global_load_dwordx4 v[68:71], v52, s[6:7] offset:16
	v_pk_mul_f32 v[74:75], v[92:93], v[106:107] op_sel_hi:[1,0]
	v_pk_mul_f32 v[76:77], v[90:91], v[106:107] op_sel_hi:[1,0]
	v_pk_mul_f32 v[78:79], v[96:97], v[106:107] op_sel_hi:[1,0]
	v_pk_mul_f32 v[80:81], v[94:95], v[106:107] op_sel_hi:[1,0]
	v_pk_mul_f32 v[76:77], v[14:15], v[76:77]
	v_pk_mul_f32 v[74:75], v[16:17], v[74:75]
	v_pk_mul_f32 v[80:81], v[10:11], v[80:81]
	v_pk_mul_f32 v[78:79], v[12:13], v[78:79]
	v_add_co_u32_e32 v72, vcc, s11, v34
	v_pk_mul_f32 v[40:41], v[40:41], v[106:107] op_sel_hi:[1,0]
	s_nop 0
	v_addc_co_u32_e32 v73, vcc, -1, v35, vcc
	v_pk_mul_f32 v[36:37], v[36:37], v[106:107] op_sel_hi:[1,0]
	v_pk_mul_f32 v[42:43], v[42:43], v[106:107] op_sel_hi:[1,0]
	v_pk_mul_f32 v[38:39], v[38:39], v[106:107] op_sel_hi:[1,0]
	v_pk_mul_f32 v[36:37], v[30:31], v[36:37]
	v_pk_mul_f32 v[40:41], v[32:33], v[40:41]
	v_pk_mul_f32 v[38:39], v[26:27], v[38:39]
	v_pk_mul_f32 v[42:43], v[28:29], v[42:43]
	v_lshl_add_u64 v[34:35], v[34:35], 0, s[0:1]
	s_waitcnt vmcnt(3)
	v_pk_add_f32 v[58:59], v[58:59], 1.0 op_sel_hi:[1,0]
	v_pk_add_f32 v[56:57], v[56:57], 1.0 op_sel_hi:[1,0]
	s_waitcnt vmcnt(2)
	v_pk_add_f32 v[62:63], v[62:63], 1.0 op_sel_hi:[1,0]
	v_pk_add_f32 v[60:61], v[60:61], 1.0 op_sel_hi:[1,0]
	s_waitcnt vmcnt(1)
	v_pk_fma_f32 v[58:59], v[58:59], v[74:75], v[66:67]
	v_pk_fma_f32 v[56:57], v[56:57], v[76:77], v[64:65]
	s_waitcnt vmcnt(0)
	v_pk_fma_f32 v[62:63], v[62:63], v[78:79], v[70:71]
	v_pk_fma_f32 v[60:61], v[60:61], v[80:81], v[68:69]
	v_cvt_pk_bf16_f32 v56, v56, v57
	v_cvt_pk_bf16_f32 v57, v58, v59
	v_cvt_pk_bf16_f32 v58, v60, v61
	v_cvt_pk_bf16_f32 v59, v62, v63
	global_store_dwordx4 v[72:73], v[56:59], off offset:-3072 sc1
	global_load_dwordx4 v[56:59], v53, s[8:9]
	s_nop 0
	global_load_dwordx4 v[60:63], v53, s[8:9] offset:16
	global_load_dwordx4 v[64:67], v53, s[6:7]
	global_load_dwordx4 v[68:71], v53, s[6:7] offset:16
	v_pk_mul_f32 v[74:75], v[100:101], v[106:107] op_sel_hi:[1,0]
	v_pk_mul_f32 v[76:77], v[98:99], v[106:107] op_sel_hi:[1,0]
	v_pk_mul_f32 v[78:79], v[104:105], v[106:107] op_sel_hi:[1,0]
	v_pk_mul_f32 v[80:81], v[102:103], v[106:107] op_sel_hi:[1,0]
	v_pk_mul_f32 v[76:77], v[22:23], v[76:77]
	v_pk_mul_f32 v[74:75], v[24:25], v[74:75]
	v_pk_mul_f32 v[80:81], v[18:19], v[80:81]
	v_pk_mul_f32 v[78:79], v[20:21], v[78:79]
	s_waitcnt vmcnt(3)
	v_pk_add_f32 v[58:59], v[58:59], 1.0 op_sel_hi:[1,0]
	v_pk_add_f32 v[56:57], v[56:57], 1.0 op_sel_hi:[1,0]
	s_waitcnt vmcnt(2)
	v_pk_add_f32 v[62:63], v[62:63], 1.0 op_sel_hi:[1,0]
	v_pk_add_f32 v[60:61], v[60:61], 1.0 op_sel_hi:[1,0]
	s_waitcnt vmcnt(1)
	v_pk_fma_f32 v[58:59], v[58:59], v[74:75], v[66:67]
	v_pk_fma_f32 v[56:57], v[56:57], v[76:77], v[64:65]
	s_waitcnt vmcnt(0)
	v_pk_fma_f32 v[62:63], v[62:63], v[78:79], v[70:71]
	v_pk_fma_f32 v[60:61], v[60:61], v[80:81], v[68:69]
	v_cvt_pk_bf16_f32 v56, v56, v57
	v_cvt_pk_bf16_f32 v57, v58, v59
	v_cvt_pk_bf16_f32 v58, v60, v61
	v_cvt_pk_bf16_f32 v59, v62, v63
	global_store_dwordx4 v[72:73], v[56:59], off offset:-2048 sc1
	global_load_dwordx4 v[56:59], v54, s[8:9]
	s_nop 0
	global_load_dwordx4 v[60:63], v54, s[8:9] offset:16
	global_load_dwordx4 v[64:67], v54, s[6:7]
	global_load_dwordx4 v[68:71], v54, s[6:7] offset:16
	s_waitcnt vmcnt(3)
	v_pk_add_f32 v[58:59], v[58:59], 1.0 op_sel_hi:[1,0]
	v_pk_add_f32 v[56:57], v[56:57], 1.0 op_sel_hi:[1,0]
	s_waitcnt vmcnt(2)
	v_pk_add_f32 v[62:63], v[62:63], 1.0 op_sel_hi:[1,0]
	v_pk_add_f32 v[60:61], v[60:61], 1.0 op_sel_hi:[1,0]
	s_waitcnt vmcnt(1)
	v_pk_fma_f32 v[40:41], v[58:59], v[40:41], v[66:67]
	v_pk_fma_f32 v[36:37], v[56:57], v[36:37], v[64:65]
	s_waitcnt vmcnt(0)
	v_pk_fma_f32 v[42:43], v[42:43], v[62:63], v[70:71]
	v_pk_fma_f32 v[38:39], v[38:39], v[60:61], v[68:69]
	v_cvt_pk_bf16_f32 v36, v36, v37
	v_cvt_pk_bf16_f32 v37, v40, v41
	v_cvt_pk_bf16_f32 v38, v38, v39
	v_cvt_pk_bf16_f32 v39, v42, v43
	global_store_dwordx4 v[72:73], v[36:39], off offset:-1024 sc1
	s_cbranch_scc1 .LBB0_439
.LBB0_440:
	v_readlane_b32 s0, v254, 0
	v_readlane_b32 s1, v254, 1
	s_cmp_gt_i32 s1, 5
	s_cselect_b64 s[0:1], -1, 0
	s_and_b64 s[4:5], s[4:5], s[0:1]
	s_andn2_b64 vcc, exec, s[4:5]
	s_cbranch_vccnz .LBB0_494
	s_waitcnt vmcnt(0)
	s_waitcnt vmcnt(0) lgkmcnt(0)
	s_barrier
	s_mov_b64 s[4:5], exec
	v_readlane_b32 s6, v254, 7
	v_readlane_b32 s7, v254, 8
	s_and_b64 s[6:7], s[4:5], s[6:7]
	s_mov_b64 exec, s[6:7]
	s_cbranch_execz .Lmy_cv4_entry
	s_cmpk_lg_i32 s3, 0x100
	s_cbranch_scc1 .Lmy_gb4_orig
	s_and_b32 s6, s2, 7
	s_lshl_b32 s6, s6, 6
	s_add_u32 s6, s6, 0x33c00
	v_mov_b32_e32 v2, s6
	v_mov_b32_e32 v3, 1
	global_atomic_add v2, v3, s[50:51]
	s_movk_i32 s7, 0x4000

.Lmy_gb4_orig:
	s_add_i32 s6, 0, 0x23fc0
	v_mov_b32_e32 v2, s6
	s_waitcnt vmcnt(0) expcnt(0) lgkmcnt(0)
	ds_read_b32 v4, v2
	s_add_i32 s6, 0, 0x23fc4
	v_mov_b32_e32 v2, s6
	ds_read_b32 v2, v2
	s_waitcnt lgkmcnt(1)
	v_cmp_ne_u32_e32 vcc, 0, v4
	s_cbranch_vccnz .LBB0_457
	v_readlane_b32 s6, v254, 2
	v_readlane_b32 s7, v254, 3
	s_load_dwordx2 s[10:11], s[6:7], 0x4
	s_add_u32 s6, s50, 0x28200
	s_addc_u32 s7, s51, 0
	s_add_u32 s8, s50, 0x28400
	s_addc_u32 s9, s51, 0
	s_waitcnt lgkmcnt(0)
	s_mul_i32 s28, s10, s3
	s_add_u32 s10, s50, 0x28500
	s_mul_i32 s28, s28, s11
	s_addc_u32 s11, s51, 0
	s_add_u32 s12, s50, 0x28600
	s_addc_u32 s13, s51, 0
	s_add_u32 s14, s50, 0x28700
	s_addc_u32 s15, s51, 0
	s_add_u32 s16, s50, 0x28800
	s_addc_u32 s17, s51, 0
	s_add_u32 s18, s50, 0x28900
	s_addc_u32 s19, s51, 0
	s_add_u32 s20, s50, 0x28a00
	s_addc_u32 s21, s51, 0
	s_add_u32 s22, s50, 0x28b00
	s_addc_u32 s23, s51, 0
	s_add_u32 s24, s50, 0x28c00
	s_addc_u32 s25, s51, 0
	s_add_u32 s26, s50, 0x28d00
	s_addc_u32 s27, s51, 0
	s_add_u32 s42, s50, 0x28e00
	s_addc_u32 s43, s51, 0
	s_add_u32 s44, s50, 0x28f00
	s_addc_u32 s45, s51, 0
	s_add_u32 s52, s50, 0x29000
	s_addc_u32 s53, s51, 0
	s_add_u32 s54, s50, 0x29100
	s_addc_u32 s55, s51, 0
	s_add_u32 s56, s50, 0x29200
	s_addc_u32 s57, s51, 0
	s_add_u32 s58, s50, 0x29300
	s_addc_u32 s59, s51, 0
	s_mov_b32 s29, 1
	v_mov_b32_e32 v18, 0
	s_branch .LBB0_445

.LBB0_781:
	v_readlane_b32 s4, v254, 0
	v_readlane_b32 s5, v254, 1
	s_cmp_lt_i32 s4, 8
	s_cselect_b64 s[4:5], -1, 0
	s_and_b64 s[4:5], s[4:5], s[0:1]
	s_andn2_b64 vcc, exec, s[4:5]
	s_cbranch_vccnz .LBB0_785
	s_cmpk_gt_i32 s70, 0x1fff
	s_cbranch_scc1 .LBB0_785
	s_mov_b32 s98, s70
	s_movk_i32 s100, 0x2000
	s_mov_b32 s101, s72
	s_cmpk_lg_i32 s3, 0x100
	s_cbranch_scc1 .Lmy_gr7
	s_and_b32 s98, s2, 7
	s_lshl_b32 s98, s98, 10
	s_add_i32 s100, s98, 0x400
	s_lshr_b32 s99, s2, 3
	s_lshl_b32 s99, s99, 3
	s_add_i32 s98, s98, s99
	v_readlane_b32 s99, v254, 10
	s_add_i32 s98, s98, s99
	s_movk_i32 s101, 0x100
.Lmy_gr7:
	s_mov_b32 s99, 0
	v_lshlrev_b32_e32 v34, 5, v1
	global_load_dwordx4 v[2:5], v34, s[66:67]
	global_load_dwordx4 v[6:9], v34, s[66:67] offset:16
	global_load_dwordx4 v[10:13], v34, s[36:37]
	global_load_dwordx4 v[14:17], v34, s[36:37] offset:16
	global_load_dwordx4 v[18:21], v34, s[66:67] offset:2048
	global_load_dwordx4 v[22:25], v34, s[66:67] offset:2064
	global_load_dwordx4 v[26:29], v34, s[36:37] offset:2048
	global_load_dwordx4 v[30:33], v34, s[36:37] offset:2064
	v_mbcnt_lo_u32_b32 v34, -1, 0
	v_mbcnt_hi_u32_b32 v34, -1, v34
	v_and_b32_e32 v35, 64, v34
	v_add_u32_e32 v35, 64, v35
	v_xor_b32_e32 v36, 1, v34
	v_cmp_lt_i32_e32 vcc, v36, v35
	s_ashr_i32 s71, s70, 31
	s_lshl_b64 s[0:1], s[98:99], 12
	v_cndmask_b32_e32 v36, v34, v36, vcc
	v_lshlrev_b32_e32 v48, 2, v36
	v_xor_b32_e32 v36, 2, v34
	v_cmp_lt_i32_e32 vcc, v36, v35
	v_lshrrev_b32_e32 v38, 2, v1
	s_ashr_i32 s73, s72, 31
	v_cndmask_b32_e32 v36, v34, v36, vcc
	v_lshlrev_b32_e32 v49, 2, v36
	v_xor_b32_e32 v36, 4, v34
	v_cmp_lt_i32_e32 vcc, v36, v35
	s_lshl_b32 s6, s101, 12
	s_mov_b32 s7, 0
	s_lshl_b32 s8, s101, 11
	s_mov_b32 s9, 0
	v_cndmask_b32_e32 v36, v34, v36, vcc
	v_lshlrev_b32_e32 v50, 2, v36
	v_xor_b32_e32 v36, 8, v34
	v_cmp_lt_i32_e32 vcc, v36, v35
	s_lshl_b32 s10, s101, 5
	s_mov_b32 s11, 0
	s_mov_b32 s12, 0x600000
	v_cndmask_b32_e32 v36, v34, v36, vcc
	v_lshlrev_b32_e32 v51, 2, v36
	v_xor_b32_e32 v36, 16, v34
	v_cmp_lt_i32_e32 vcc, v36, v35
	s_mov_b32 s13, 0x640000
	s_mov_b32 s14, 0x680000
	v_cndmask_b32_e32 v36, v34, v36, vcc
	v_lshlrev_b32_e32 v52, 2, v36
	v_xor_b32_e32 v36, 32, v34
	v_cmp_lt_i32_e32 vcc, v36, v35
	v_mov_b32_e32 v35, s1
	s_mov_b32 s15, 0x19400000
	v_cndmask_b32_e32 v34, v34, v36, vcc
	v_lshlrev_b32_e32 v36, 4, v1
	v_lshlrev_b32_e32 v53, 2, v34
	v_or_b32_e32 v34, s0, v36
	s_lshl_b64 s[0:1], s[98:99], 11
	v_or_b32_e32 v36, s0, v36
	v_mov_b32_e32 v37, s1
	s_lshl_b64 s[0:1], s[98:99], 5
	v_and_or_b32 v38, v38, 12, s0
	v_mov_b32_e32 v39, s1
	v_or_b32_e32 v40, 16, v38
	v_mov_b32_e32 v41, s1
	s_mov_b32 s16, 0x1a400000
	s_mov_b32 s17, 0x1b400000
	v_mov_b32_e32 v54, 0x358637bd
	s_mov_b32 s18, 0xac00000
	s_mov_b32 s19, s98
.LBB0_784:
	v_lshl_add_u64 v[44:45], s[50:51], 0, v[36:37]
	v_add_co_u32_e64 v86, s[0:1], s15, v44
	v_lshl_add_u64 v[46:47], s[50:51], 0, v[40:41]
	s_nop 0
	v_addc_co_u32_e64 v87, s[0:1], 0, v45, s[0:1]
	v_add_co_u32_e64 v76, s[0:1], s16, v44
	v_add_co_u32_e32 v84, vcc, 0x18400000, v44
	s_nop 0
	v_addc_co_u32_e64 v77, s[0:1], 0, v45, s[0:1]
	v_add_co_u32_e64 v78, s[0:1], s17, v44
	v_lshl_add_u64 v[42:43], s[50:51], 0, v[38:39]
	s_nop 0
	v_addc_co_u32_e64 v79, s[0:1], 0, v45, s[0:1]
	v_add_co_u32_e64 v80, s[0:1], s12, v46
	v_addc_co_u32_e32 v85, vcc, 0, v45, vcc
	s_nop 0
	v_addc_co_u32_e64 v81, s[0:1], 0, v47, s[0:1]
	v_add_co_u32_e64 v82, s[0:1], s13, v46
	v_lshl_add_u64 v[56:57], s[50:51], 0, v[34:35]
	s_nop 0
	v_addc_co_u32_e64 v83, s[0:1], 0, v47, s[0:1]
	v_add_co_u32_e64 v88, s[0:1], s14, v46
	v_add_co_u32_e32 v44, vcc, 0x600000, v42
	s_nop 0
	v_addc_co_u32_e64 v89, s[0:1], 0, v47, s[0:1]
	v_add_co_u32_e64 v46, s[0:1], s18, v56
	v_addc_co_u32_e32 v45, vcc, 0, v43, vcc
	s_nop 0
	v_addc_co_u32_e64 v47, s[0:1], 0, v57, s[0:1]
	global_load_dword v55, v[80:81], off
	global_load_dword v91, v[82:83], off
	global_load_dword v95, v[88:89], off
	global_load_dwordx4 v[56:59], v[86:87], off offset:1024 nt
	global_load_dwordx4 v[60:63], v[76:77], off offset:1024 nt
	global_load_dwordx4 v[64:67], v[78:79], off offset:1024 nt
	global_load_dwordx4 v[68:71], v[76:77], off nt
	global_load_dwordx4 v[72:75], v[78:79], off nt
	s_nop 0
	global_load_dwordx4 v[76:79], v[84:85], off offset:1024 nt
	global_load_dwordx4 v[80:83], v[84:85], off nt
	v_add_co_u32_e32 v84, vcc, 0x640000, v42
	global_load_dword v138, v[44:45], off
	s_nop 0
	v_addc_co_u32_e32 v85, vcc, 0, v43, vcc
	v_add_co_u32_e32 v88, vcc, 0x680000, v42
	s_add_i32 s19, s19, s101
	s_nop 0
	v_addc_co_u32_e32 v89, vcc, 0, v43, vcc
	global_load_dword v139, v[84:85], off
	global_load_dword v140, v[88:89], off
	global_load_dwordx4 v[42:45], v[86:87], off nt
	v_lshl_add_u64 v[34:35], v[34:35], 0, s[6:7]
	v_lshl_add_u64 v[36:37], v[36:37], 0, s[8:9]
	v_lshl_add_u64 v[38:39], v[38:39], 0, s[10:11]
	v_lshl_add_u64 v[40:41], v[40:41], 0, s[10:11]
	s_cmp_lt_i32 s19, s100
	s_waitcnt vmcnt(0)
	v_max3_f32 v99, v55, v91, v95
	v_lshlrev_b32_e32 v102, 16, v58
	v_sub_f32_e32 v55, v55, v99
	v_and_b32_e32 v103, 0xffff0000, v62
	v_mul_f32_e32 v55, 0x3fb8aa3b, v55
	v_lshlrev_b32_e32 v96, 16, v73
	v_and_b32_e32 v97, 0xffff0000, v73
	v_and_b32_e32 v73, 0xffff0000, v58
	v_sub_f32_e32 v58, v91, v99
	v_lshlrev_b32_e32 v118, 16, v80
	v_and_b32_e32 v119, 0xffff0000, v80
	v_lshlrev_b32_e32 v100, 16, v72
	v_and_b32_e32 v101, 0xffff0000, v72
	v_lshlrev_b32_e32 v72, 16, v62
	v_sub_f32_e32 v62, v95, v99
	v_lshlrev_b32_e32 v114, 16, v83
	v_and_b32_e32 v115, 0xffff0000, v83
	v_lshlrev_b32_e32 v116, 16, v82
	v_and_b32_e32 v117, 0xffff0000, v82
	v_lshlrev_b32_e32 v82, 16, v81
	v_and_b32_e32 v83, 0xffff0000, v81
	v_mul_f32_e32 v58, 0x3fb8aa3b, v58
	v_pk_mul_f32 v[128:129], v[118:119], v[118:119]
	v_mul_f32_e32 v62, 0x3fb8aa3b, v62
	v_pk_mul_f32 v[126:127], v[82:83], v[82:83]
	v_exp_f32_e32 v136, v55
	v_exp_f32_e32 v137, v58
	v_add_f32_e32 v128, v128, v129
	v_max3_f32 v129, v138, v139, v140
	v_and_b32_e32 v85, 0xffff0000, v59
	v_lshlrev_b32_e32 v84, 16, v63
	v_and_b32_e32 v87, 0xffff0000, v63
	v_lshlrev_b32_e32 v86, 16, v59
	v_and_b32_e32 v89, 0xffff0000, v67
	v_lshlrev_b32_e32 v88, 16, v67
	v_lshlrev_b32_e32 v90, 16, v71
	v_and_b32_e32 v59, 0xffff0000, v71
	v_lshlrev_b32_e32 v92, 16, v75
	v_and_b32_e32 v93, 0xffff0000, v75
	v_lshlrev_b32_e32 v94, 16, v70
	v_and_b32_e32 v63, 0xffff0000, v70
	v_lshlrev_b32_e32 v70, 16, v74
	v_and_b32_e32 v71, 0xffff0000, v74
	v_lshlrev_b32_e32 v74, 16, v69
	v_and_b32_e32 v67, 0xffff0000, v69
	v_lshlrev_b32_e32 v98, 16, v68
	v_and_b32_e32 v69, 0xffff0000, v68
	v_lshlrev_b32_e32 v104, 16, v66
	v_and_b32_e32 v105, 0xffff0000, v66
	v_exp_f32_e32 v55, v62
	v_and_b32_e32 v95, 0xffff0000, v44
	v_lshlrev_b32_e32 v62, 16, v44
	v_and_b32_e32 v75, 0xffff0000, v43
	v_lshlrev_b32_e32 v66, 16, v43
	v_and_b32_e32 v99, 0xffff0000, v42
	v_lshlrev_b32_e32 v68, 16, v42
	v_add_f32_e32 v42, v126, v128
	v_sub_f32_e32 v43, v138, v129
	v_sub_f32_e32 v44, v139, v129
	v_pk_mul_f32 v[124:125], v[116:117], v[116:117]
	v_and_b32_e32 v91, 0xffff0000, v45
	v_lshlrev_b32_e32 v58, 16, v45
	v_sub_f32_e32 v45, v140, v129
	v_add_f32_e32 v42, v127, v42
	v_mul_f32_e32 v43, 0x3fb8aa3b, v43
	v_mul_f32_e32 v44, 0x3fb8aa3b, v44
	v_mul_f32_e32 v45, 0x3fb8aa3b, v45
	v_add_f32_e32 v124, v124, v42
	v_exp_f32_e32 v43, v43
	v_exp_f32_e32 v42, v44
	v_pk_mul_f32 v[122:123], v[114:115], v[114:115]
	v_exp_f32_e32 v45, v45
	v_add_f32_e32 v44, v136, v137
	v_add_f32_e32 v124, v125, v124
	v_lshlrev_b32_e32 v120, 16, v76
	v_and_b32_e32 v121, 0xffff0000, v76
	v_add_f32_e32 v125, v55, v44
	v_add_f32_e32 v44, v122, v124
	v_pk_mul_f32 v[134:135], v[120:121], v[120:121]
	v_div_scale_f32 v122, s[0:1], v125, v125, 1.0
	v_add_f32_e32 v44, v123, v44
	v_lshlrev_b32_e32 v106, 16, v61
	v_and_b32_e32 v107, 0xffff0000, v57
	v_lshlrev_b32_e32 v108, 16, v57
	v_and_b32_e32 v109, 0xffff0000, v61
	v_lshlrev_b32_e32 v110, 16, v65
	v_and_b32_e32 v111, 0xffff0000, v65
	v_lshlrev_b32_e32 v112, 16, v60
	v_and_b32_e32 v57, 0xffff0000, v60
	v_lshlrev_b32_e32 v60, 16, v64
	v_and_b32_e32 v61, 0xffff0000, v64
	v_and_b32_e32 v64, 0xffff0000, v79
	v_lshlrev_b32_e32 v65, 16, v79
	v_lshlrev_b32_e32 v80, 16, v78
	v_and_b32_e32 v81, 0xffff0000, v78
	v_lshlrev_b32_e32 v78, 16, v77
	v_and_b32_e32 v79, 0xffff0000, v77
	v_rcp_f32_e32 v123, v122
	v_add_f32_e32 v44, v44, v134
	v_add_f32_e32 v126, v43, v42
	v_pk_mul_f32 v[132:133], v[78:79], v[78:79]
	v_add_f32_e32 v44, v135, v44
	v_add_f32_e32 v126, v45, v126
	v_add_f32_e32 v44, v132, v44
	v_div_scale_f32 v127, s[20:21], v126, v126, 1.0
	v_pk_mul_f32 v[130:131], v[80:81], v[80:81]
	v_add_f32_e32 v44, v133, v44
	v_rcp_f32_e32 v129, v127
	v_fma_f32 v132, -v122, v123, 1.0
	v_add_f32_e32 v44, v130, v44
	v_pk_mul_f32 v[76:77], v[64:65], v[64:65]
	v_div_scale_f32 v124, s[0:1], 1.0, v125, 1.0
	v_fmac_f32_e32 v123, v132, v123
	v_add_f32_e32 v44, v131, v44
	v_mul_f32_e32 v130, v124, v123
	v_add_f32_e32 v44, v77, v44
	v_fma_f32 v77, -v122, v130, v124
	v_add_f32_e32 v44, v76, v44
	v_fma_f32 v76, -v127, v129, 1.0
	v_div_scale_f32 v128, vcc, 1.0, v126, 1.0
	v_fmac_f32_e32 v130, v77, v123
	ds_bpermute_b32 v77, v48, v44
	v_fmac_f32_e32 v129, v76, v129
	v_fma_f32 v76, -v122, v130, v124
	v_mul_f32_e32 v122, v128, v129
	v_fma_f32 v124, -v127, v122, v128
	v_fmac_f32_e32 v122, v124, v129
	v_fma_f32 v124, -v127, v122, v128
	s_waitcnt lgkmcnt(0)
	v_add_f32_e32 v77, v44, v77
	v_div_fmas_f32 v44, v124, v129, v122
	s_mov_b64 vcc, s[0:1]
	ds_bpermute_b32 v124, v49, v77
	v_div_fixup_f32 v44, v44, v126, 1.0
	v_div_fmas_f32 v122, v76, v123, v130
	v_div_fixup_f32 v122, v122, v125, 1.0
	v_pk_mul_f32 v[42:43], v[42:43], v[44:45] op_sel_hi:[1,0]
	v_mul_f32_e32 v76, v45, v44
	v_mul_f32_e32 v44, v55, v122
	v_pk_mul_f32 v[122:123], v[136:137], v[122:123] op_sel_hi:[1,0]
	v_pk_mul_f32 v[58:59], v[42:43], v[58:59] op_sel:[1,0] op_sel_hi:[0,1]
	v_pk_mul_f32 v[62:63], v[42:43], v[62:63] op_sel:[1,0] op_sel_hi:[0,1]
	v_pk_mul_f32 v[66:67], v[42:43], v[66:67] op_sel:[1,0] op_sel_hi:[0,1]
	v_pk_mul_f32 v[68:69], v[42:43], v[68:69] op_sel:[1,0] op_sel_hi:[0,1]
	v_pk_mul_f32 v[84:85], v[122:123], v[84:85] op_sel:[1,0] op_sel_hi:[0,1]
	v_pk_fma_f32 v[58:59], v[42:43], v[90:91], v[58:59]
	v_pk_fma_f32 v[62:63], v[42:43], v[94:95], v[62:63]
	v_pk_fma_f32 v[66:67], v[42:43], v[74:75], v[66:67]
	v_pk_fma_f32 v[42:43], v[42:43], v[98:99], v[68:69]
	v_pk_mul_f32 v[68:69], v[122:123], v[102:103]
	v_pk_fma_f32 v[84:85], v[122:123], v[86:87], v[84:85]
	v_pk_fma_f32 v[62:63], v[76:77], v[70:71], v[62:63] op_sel_hi:[0,1,1]
	v_pk_fma_f32 v[70:71], v[76:77], v[100:101], v[42:43] op_sel_hi:[0,1,1]
	v_pk_fma_f32 v[66:67], v[76:77], v[96:97], v[66:67] op_sel_hi:[0,1,1]
	s_waitcnt lgkmcnt(0)
	v_add_f32_e32 v55, v77, v124
	v_pk_fma_f32 v[42:43], v[122:123], v[72:73], v[68:69] op_sel:[1,0,0] op_sel_hi:[0,1,1]
	v_pk_fma_f32 v[68:69], v[44:45], v[88:89], v[84:85] op_sel_hi:[0,1,1]
	v_pk_mul_f32 v[84:85], v[70:71], v[70:71]
	v_pk_fma_f32 v[86:87], v[76:77], v[92:93], v[58:59] op_sel_hi:[0,1,1]
	v_pk_mul_f32 v[76:77], v[66:67], v[66:67]
	ds_bpermute_b32 v92, v50, v55
	v_add_f32_e32 v84, v84, v85
	v_pk_mul_f32 v[74:75], v[122:123], v[108:109]
	v_add_f32_e32 v76, v76, v84
	v_and_b32_e32 v113, 0xffff0000, v56
	v_lshlrev_b32_e32 v56, 16, v56
	v_pk_fma_f32 v[58:59], v[122:123], v[106:107], v[74:75] op_sel:[1,0,0] op_sel_hi:[0,1,1]
	v_pk_mul_f32 v[74:75], v[62:63], v[62:63]
	v_add_f32_e32 v76, v77, v76
	v_pk_mul_f32 v[56:57], v[122:123], v[56:57]
	v_add_f32_e32 v74, v74, v76
	v_pk_fma_f32 v[56:57], v[122:123], v[112:113], v[56:57] op_sel:[1,0,0] op_sel_hi:[0,1,1]
	v_pk_mul_f32 v[72:73], v[86:87], v[86:87]
	v_add_f32_e32 v74, v75, v74
	v_pk_fma_f32 v[60:61], v[44:45], v[60:61], v[56:57] op_sel_hi:[0,1,1]
	s_waitcnt lgkmcnt(0)
	v_add_f32_e32 v55, v55, v92
	v_add_f32_e32 v72, v72, v74
	v_pk_fma_f32 v[90:91], v[44:45], v[110:111], v[58:59] op_sel_hi:[0,1,1]
	v_pk_mul_f32 v[58:59], v[60:61], v[60:61]
	ds_bpermute_b32 v75, v51, v55
	v_add_f32_e32 v72, v73, v72
	v_add_f32_e32 v58, v72, v58
	v_pk_mul_f32 v[56:57], v[90:91], v[90:91]
	v_add_f32_e32 v58, v59, v58
	v_pk_fma_f32 v[88:89], v[44:45], v[104:105], v[42:43] op_sel_hi:[0,1,1]
	v_add_f32_e32 v56, v56, v58
	v_pk_mul_f32 v[44:45], v[88:89], v[88:89]
	v_add_f32_e32 v56, v57, v56
	s_waitcnt lgkmcnt(0)
	v_add_f32_e32 v55, v55, v75
	v_add_f32_e32 v44, v44, v56
	v_pk_mul_f32 v[42:43], v[68:69], v[68:69]
	ds_bpermute_b32 v57, v52, v55
	v_add_f32_e32 v44, v45, v44
	v_add_f32_e32 v42, v42, v44
	v_add_f32_e32 v42, v43, v42
	ds_bpermute_b32 v43, v48, v42
	s_waitcnt lgkmcnt(1)
	v_add_f32_e32 v44, v55, v57
	ds_bpermute_b32 v45, v53, v44
	s_waitcnt lgkmcnt(1)
	v_add_f32_e32 v43, v42, v43
	ds_bpermute_b32 v55, v49, v43
	s_waitcnt lgkmcnt(1)
	v_add_f32_e32 v42, v44, v45
	v_fmamk_f32 v42, v42, 0x3a800000, v54
	v_rsq_f32_e32 v42, v42
	s_waitcnt lgkmcnt(0)
	v_add_f32_e32 v55, v43, v55
	ds_bpermute_b32 v84, v50, v55
	v_pk_mul_f32 v[44:45], v[42:43], v[118:119] op_sel_hi:[0,1]
	v_pk_mul_f32 v[56:57], v[42:43], v[82:83] op_sel_hi:[0,1]
	v_pk_mul_f32 v[58:59], v[42:43], v[116:117] op_sel_hi:[0,1]
	v_pk_mul_f32 v[72:73], v[42:43], v[114:115] op_sel_hi:[0,1]
	v_pk_mul_f32 v[74:75], v[42:43], v[120:121] op_sel_hi:[0,1]
	v_pk_mul_f32 v[76:77], v[42:43], v[78:79] op_sel_hi:[0,1]
	v_pk_mul_f32 v[78:79], v[42:43], v[80:81] op_sel_hi:[0,1]
	v_pk_mul_f32 v[42:43], v[42:43], v[64:65] op_sel_hi:[0,1]
	v_pk_mul_f32 v[44:45], v[2:3], v[44:45]
	v_pk_mul_f32 v[56:57], v[4:5], v[56:57]
	v_pk_mul_f32 v[58:59], v[6:7], v[58:59]
	v_pk_mul_f32 v[64:65], v[8:9], v[72:73]
	v_pk_mul_f32 v[72:73], v[18:19], v[74:75]
	v_pk_mul_f32 v[74:75], v[20:21], v[76:77]
	v_pk_mul_f32 v[76:77], v[22:23], v[78:79]
	v_pk_mul_f32 v[78:79], v[24:25], v[42:43] op_sel:[0,1] op_sel_hi:[1,0]
	v_cvt_pk_bf16_f32 v42, v44, v45
	v_cvt_pk_bf16_f32 v43, v56, v57
	v_cvt_pk_bf16_f32 v44, v58, v59
	v_cvt_pk_bf16_f32 v45, v64, v65
	v_cvt_pk_bf16_f32 v56, v72, v73
	v_cvt_pk_bf16_f32 v57, v74, v75
	v_cvt_pk_bf16_f32 v58, v76, v77
	v_cvt_pk_bf16_f32 v59, v78, v79
	global_store_dwordx4 v[46:47], v[42:45], off sc1
	global_store_dwordx4 v[46:47], v[56:59], off offset:1024 sc1
	s_waitcnt lgkmcnt(0)
	v_add_f32_e32 v42, v55, v84
	ds_bpermute_b32 v43, v51, v42
	s_waitcnt lgkmcnt(0)
	v_add_f32_e32 v42, v42, v43
	ds_bpermute_b32 v43, v52, v42
	s_waitcnt lgkmcnt(0)
	v_add_f32_e32 v42, v42, v43
	ds_bpermute_b32 v43, v53, v42
	s_waitcnt lgkmcnt(0)
	v_add_f32_e32 v42, v42, v43
	v_fmamk_f32 v42, v42, 0x3a800000, v54
	v_rsq_f32_e32 v42, v42
	s_nop 0
	v_pk_mul_f32 v[44:45], v[70:71], v[42:43] op_sel_hi:[1,0]
	v_pk_mul_f32 v[56:57], v[66:67], v[42:43] op_sel_hi:[1,0]
	v_pk_mul_f32 v[58:59], v[62:63], v[42:43] op_sel_hi:[1,0]
	v_pk_mul_f32 v[62:63], v[86:87], v[42:43] op_sel_hi:[1,0]
	v_pk_mul_f32 v[60:61], v[60:61], v[42:43] op_sel_hi:[1,0]
	v_pk_mul_f32 v[64:65], v[90:91], v[42:43] op_sel_hi:[1,0]
	v_pk_mul_f32 v[66:67], v[88:89], v[42:43] op_sel_hi:[1,0]
	v_pk_mul_f32 v[42:43], v[68:69], v[42:43] op_sel_hi:[1,0]
	v_pk_mul_f32 v[44:45], v[10:11], v[44:45]
	v_pk_mul_f32 v[56:57], v[12:13], v[56:57]
	v_pk_mul_f32 v[58:59], v[14:15], v[58:59]
	v_pk_mul_f32 v[62:63], v[16:17], v[62:63]
	v_pk_mul_f32 v[60:61], v[26:27], v[60:61]
	v_pk_mul_f32 v[64:65], v[28:29], v[64:65]
	v_pk_mul_f32 v[66:67], v[30:31], v[66:67]
	v_pk_mul_f32 v[68:69], v[32:33], v[42:43]
	v_cvt_pk_bf16_f32 v42, v44, v45
	v_cvt_pk_bf16_f32 v43, v56, v57
	v_cvt_pk_bf16_f32 v44, v58, v59
	v_cvt_pk_bf16_f32 v45, v62, v63
	v_cvt_pk_bf16_f32 v56, v60, v61
	v_cvt_pk_bf16_f32 v57, v64, v65
	v_cvt_pk_bf16_f32 v58, v66, v67
	v_cvt_pk_bf16_f32 v59, v68, v69
	global_store_dwordx4 v[46:47], v[42:45], off offset:2048 sc1
	global_store_dwordx4 v[46:47], v[56:59], off offset:3072 sc1
	s_cbranch_scc1 .LBB0_784
.LBB0_785:
	v_readlane_b32 s0, v254, 0
	v_readlane_b32 s1, v254, 1
	s_cmp_gt_i32 s1, 8
	s_cselect_b64 s[0:1], -1, 0
	s_and_b64 s[4:5], s[4:5], s[0:1]
	s_andn2_b64 vcc, exec, s[4:5]
	s_cbranch_vccnz .LBB0_839
	s_waitcnt vmcnt(0)
	s_waitcnt vmcnt(0)
	s_barrier
	s_mov_b64 s[4:5], exec
	v_readlane_b32 s6, v254, 7
	v_readlane_b32 s7, v254, 8
	s_and_b64 s[6:7], s[4:5], s[6:7]
	s_mov_b64 exec, s[6:7]
	s_cbranch_execz .Lmy_cv7_entry
	s_cmpk_lg_i32 s3, 0x100
	s_cbranch_scc1 .Lmy_gb7_orig
	s_and_b32 s6, s2, 7
	s_lshl_b32 s6, s6, 6
	s_add_u32 s6, s6, 0x34200
	v_mov_b32_e32 v2, s6
	v_mov_b32_e32 v3, 1
	global_atomic_add v2, v3, s[50:51]
	s_movk_i32 s7, 0x4000

.Lmy_gb7_orig:
	s_add_i32 s6, 0, 0x23fc0
	v_mov_b32_e32 v2, s6
	s_waitcnt vmcnt(0) expcnt(0) lgkmcnt(0)
	ds_read_b32 v4, v2
	s_add_i32 s6, 0, 0x23fc4
	v_mov_b32_e32 v2, s6
	ds_read_b32 v2, v2
	s_waitcnt lgkmcnt(1)
	v_cmp_ne_u32_e32 vcc, 0, v4
	s_cbranch_vccnz .LBB0_802
	v_readlane_b32 s6, v254, 2
	v_readlane_b32 s7, v254, 3
	s_load_dwordx2 s[10:11], s[6:7], 0x4
	s_add_u32 s6, s50, 0x28200
	s_addc_u32 s7, s51, 0
	s_add_u32 s8, s50, 0x28400
	s_addc_u32 s9, s51, 0
	s_waitcnt lgkmcnt(0)
	s_mul_i32 s28, s10, s3
	s_add_u32 s10, s50, 0x28500
	s_mul_i32 s28, s28, s11
	s_addc_u32 s11, s51, 0
	s_add_u32 s12, s50, 0x28600
	s_addc_u32 s13, s51, 0
	s_add_u32 s14, s50, 0x28700
	s_addc_u32 s15, s51, 0
	s_add_u32 s16, s50, 0x28800
	s_addc_u32 s17, s51, 0
	s_add_u32 s18, s50, 0x28900
	s_addc_u32 s19, s51, 0
	s_add_u32 s20, s50, 0x28a00
	s_addc_u32 s21, s51, 0
	s_add_u32 s22, s50, 0x28b00
	s_addc_u32 s23, s51, 0
	s_add_u32 s24, s50, 0x28c00
	s_addc_u32 s25, s51, 0
	s_add_u32 s26, s50, 0x28d00
	s_addc_u32 s27, s51, 0
	s_add_u32 s36, s50, 0x28e00
	s_addc_u32 s37, s51, 0
	s_add_u32 s42, s50, 0x28f00
	s_addc_u32 s43, s51, 0
	s_add_u32 s44, s50, 0x29000
	s_addc_u32 s45, s51, 0
	s_add_u32 s52, s50, 0x29100
	s_addc_u32 s53, s51, 0
	s_add_u32 s54, s50, 0x29200
	s_addc_u32 s55, s51, 0
	s_add_u32 s56, s50, 0x29300
	s_addc_u32 s57, s51, 0
	s_mov_b32 s29, 1
	v_mov_b32_e32 v18, 0
	s_branch .LBB0_790

.LBB0_860:
	v_lshl_or_b32 v130, s67, 8, v172
	v_ashrrev_i32_e32 v131, 31, v130
	v_lshl_add_u32 v168, s42, 8, v170
	v_lshlrev_b64 v[162:163], 1, v[130:131]
	v_ashrrev_i32_e32 v169, 31, v168
	v_lshl_add_u64 v[164:165], s[10:11], 0, v[162:163]
	v_lshlrev_b64 v[166:167], 12, v[168:169]
	v_lshl_add_u64 v[132:133], v[164:165], 0, v[166:167]
	global_load_dwordx4 v[176:179], v[132:133], off nt
	global_load_dwordx4 v[180:183], v[132:133], off offset:256 nt
	v_or_b32_e32 v132, 16, v168
	v_ashrrev_i32_e32 v133, 31, v132
	v_lshlrev_b64 v[196:197], 12, v[132:133]
	v_lshl_add_u64 v[188:189], v[164:165], 0, v[196:197]
	s_ashr_i32 s23, s42, 4
	global_load_dwordx4 v[184:187], v[188:189], off nt
	s_mul_hi_i32 s25, s23, 0x12000
	s_mul_i32 s23, s23, 0x12000
	s_add_u32 s30, s60, s23
	s_addc_u32 s31, s61, s25
	v_lshl_add_u64 v[130:131], v[130:131], 2, s[30:31]
	global_load_dwordx4 v[142:145], v[130:131], off
	global_load_dwordx4 v[138:141], v[130:131], off offset:16
	global_load_dwordx4 v[134:137], v[130:131], off offset:512
	s_nop 0
	global_load_dwordx4 v[130:133], v[130:131], off offset:528
	s_nop 0
	global_load_dwordx4 v[188:191], v[188:189], off offset:256 nt
	v_or_b32_e32 v192, 32, v168
	v_ashrrev_i32_e32 v193, 31, v192
	v_lshlrev_b64 v[208:209], 12, v[192:193]
	v_lshl_add_u64 v[198:199], v[164:165], 0, v[208:209]
	global_load_dwordx4 v[192:195], v[198:199], off nt
	v_or_b32_e32 v168, 48, v168
	v_ashrrev_i32_e32 v169, 31, v168
	v_lshlrev_b64 v[168:169], 12, v[168:169]
	v_lshl_add_u64 v[200:201], s[10:11], 0, v[166:167]
	v_lshl_add_u64 v[204:205], v[164:165], 0, v[168:169]
	v_lshl_add_u64 v[210:211], v[200:201], 0, v[162:163]
	v_lshl_add_u64 v[212:213], s[10:11], 0, v[196:197]
	global_load_dwordx4 v[196:199], v[198:199], off offset:256 nt
	s_nop 0
	global_load_dwordx4 v[200:203], v[204:205], off nt
	s_nop 0
	global_load_dwordx4 v[204:207], v[204:205], off offset:256 nt
	v_lshl_add_u64 v[212:213], v[212:213], 0, v[162:163]
	s_andn2_b64 vcc, exec, s[0:1]
	s_mov_b64 s[0:1], -1
	s_waitcnt vmcnt(0)
	v_cvt_f32_f16_e32 v214, v176
	v_cvt_f32_f16_sdwa v215, v176 dst_sel:DWORD dst_unused:UNUSED_PAD src0_sel:WORD_1
	v_cvt_f32_f16_e32 v176, v177
	v_cvt_f32_f16_sdwa v177, v177 dst_sel:DWORD dst_unused:UNUSED_PAD src0_sel:WORD_1
	v_cvt_f32_f16_e32 v216, v178
	v_cvt_f32_f16_sdwa v217, v178 dst_sel:DWORD dst_unused:UNUSED_PAD src0_sel:WORD_1
	v_cvt_f32_f16_e32 v178, v179
	v_cvt_f32_f16_sdwa v179, v179 dst_sel:DWORD dst_unused:UNUSED_PAD src0_sel:WORD_1
	v_cvt_f32_f16_e32 v218, v180
	v_cvt_f32_f16_sdwa v219, v180 dst_sel:DWORD dst_unused:UNUSED_PAD src0_sel:WORD_1
	v_cvt_f32_f16_e32 v180, v181
	v_cvt_f32_f16_sdwa v181, v181 dst_sel:DWORD dst_unused:UNUSED_PAD src0_sel:WORD_1
	v_cvt_f32_f16_e32 v220, v182
	v_cvt_f32_f16_sdwa v221, v182 dst_sel:DWORD dst_unused:UNUSED_PAD src0_sel:WORD_1
	v_cvt_f32_f16_e32 v182, v183
	v_cvt_f32_f16_sdwa v183, v183 dst_sel:DWORD dst_unused:UNUSED_PAD src0_sel:WORD_1
	v_cvt_f32_f16_e32 v222, v184
	v_cvt_f32_f16_sdwa v223, v184 dst_sel:DWORD dst_unused:UNUSED_PAD src0_sel:WORD_1
	v_cvt_f32_f16_e32 v184, v185
	v_cvt_f32_f16_sdwa v185, v185 dst_sel:DWORD dst_unused:UNUSED_PAD src0_sel:WORD_1
	v_cvt_f32_f16_e32 v224, v186
	v_cvt_f32_f16_sdwa v225, v186 dst_sel:DWORD dst_unused:UNUSED_PAD src0_sel:WORD_1
	v_cvt_f32_f16_e32 v186, v187
	v_cvt_f32_f16_sdwa v187, v187 dst_sel:DWORD dst_unused:UNUSED_PAD src0_sel:WORD_1
	v_pk_fma_f32 v[128:129], v[128:129], v[144:145], v[176:177]
	v_pk_fma_f32 v[126:127], v[126:127], v[142:143], v[214:215]
	v_pk_fma_f32 v[124:125], v[124:125], v[140:141], v[178:179]
	v_pk_fma_f32 v[122:123], v[122:123], v[138:139], v[216:217]
	v_pk_fma_f32 v[112:113], v[112:113], v[136:137], v[180:181]
	v_pk_fma_f32 v[110:111], v[110:111], v[134:135], v[218:219]
	v_pk_fma_f32 v[176:177], v[108:109], v[132:133], v[182:183]
	v_pk_fma_f32 v[178:179], v[106:107], v[130:131], v[220:221]
	v_pk_fma_f32 v[120:121], v[120:121], v[144:145], v[184:185]
	v_pk_fma_f32 v[118:119], v[118:119], v[142:143], v[222:223]
	v_pk_fma_f32 v[180:181], v[116:117], v[140:141], v[186:187]
	v_pk_fma_f32 v[116:117], v[114:115], v[138:139], v[224:225]
	v_cvt_pk_f16_f32 v106, v126, v127
	v_cvt_pk_f16_f32 v107, v128, v129
	v_cvt_pk_f16_f32 v108, v122, v123
	v_cvt_pk_f16_f32 v109, v124, v125
	v_cvt_pk_f16_f32 v110, v110, v111
	v_cvt_pk_f16_f32 v111, v112, v113
	v_cvt_pk_f16_f32 v112, v178, v179
	v_cvt_pk_f16_f32 v113, v176, v177
	v_cvt_pk_f16_f32 v114, v118, v119
	v_cvt_pk_f16_f32 v115, v120, v121
	v_cvt_pk_f16_f32 v116, v116, v117
	v_cvt_pk_f16_f32 v117, v180, v181
	global_store_dwordx4 v[210:211], v[106:109], off sc1
	global_store_dwordx4 v[210:211], v[110:113], off offset:256 sc1
	global_store_dwordx4 v[212:213], v[114:117], off sc1
	v_cvt_f32_f16_e32 v106, v188
	v_cvt_f32_f16_sdwa v107, v188 dst_sel:DWORD dst_unused:UNUSED_PAD src0_sel:WORD_1
	v_cvt_f32_f16_e32 v108, v189
	v_cvt_f32_f16_sdwa v109, v189 dst_sel:DWORD dst_unused:UNUSED_PAD src0_sel:WORD_1
	v_cvt_f32_f16_e32 v110, v190
	v_cvt_f32_f16_e32 v112, v191
	v_cvt_f32_f16_sdwa v113, v191 dst_sel:DWORD dst_unused:UNUSED_PAD src0_sel:WORD_1
	v_cvt_f32_f16_sdwa v111, v190 dst_sel:DWORD dst_unused:UNUSED_PAD src0_sel:WORD_1
	v_pk_fma_f32 v[104:105], v[104:105], v[136:137], v[108:109]
	v_pk_fma_f32 v[102:103], v[102:103], v[134:135], v[106:107]
	v_pk_fma_f32 v[106:107], v[100:101], v[132:133], v[112:113]
	v_pk_fma_f32 v[100:101], v[98:99], v[130:131], v[110:111]
	v_cvt_pk_f16_f32 v98, v102, v103
	v_cvt_pk_f16_f32 v99, v104, v105
	v_cvt_pk_f16_f32 v100, v100, v101
	v_cvt_pk_f16_f32 v101, v106, v107
	global_store_dwordx4 v[212:213], v[98:101], off offset:256 sc1
	v_cvt_f32_f16_e32 v102, v194
	v_cvt_f32_f16_e32 v104, v195
	v_cvt_f32_f16_e32 v98, v192
	v_cvt_f32_f16_sdwa v99, v192 dst_sel:DWORD dst_unused:UNUSED_PAD src0_sel:WORD_1
	v_cvt_f32_f16_e32 v100, v193
	v_cvt_f32_f16_sdwa v101, v193 dst_sel:DWORD dst_unused:UNUSED_PAD src0_sel:WORD_1
	v_cvt_f32_f16_sdwa v105, v195 dst_sel:DWORD dst_unused:UNUSED_PAD src0_sel:WORD_1
	v_cvt_f32_f16_sdwa v103, v194 dst_sel:DWORD dst_unused:UNUSED_PAD src0_sel:WORD_1
	v_pk_fma_f32 v[94:95], v[94:95], v[142:143], v[98:99]
	v_pk_fma_f32 v[96:97], v[96:97], v[144:145], v[100:101]
	v_pk_fma_f32 v[98:99], v[92:93], v[140:141], v[104:105]
	v_pk_fma_f32 v[92:93], v[90:91], v[138:139], v[102:103]
	v_cvt_pk_f16_f32 v90, v94, v95
	v_lshl_add_u64 v[94:95], s[10:11], 0, v[208:209]
	v_cvt_pk_f16_f32 v91, v96, v97
	v_cvt_pk_f16_f32 v92, v92, v93
	v_cvt_pk_f16_f32 v93, v98, v99
	v_lshl_add_u64 v[94:95], v[94:95], 0, v[162:163]
	global_store_dwordx4 v[94:95], v[90:93], off sc1
	v_cvt_f32_f16_e32 v96, v198
	v_cvt_f32_f16_e32 v98, v199
	v_cvt_f32_f16_e32 v90, v196
	v_cvt_f32_f16_sdwa v91, v196 dst_sel:DWORD dst_unused:UNUSED_PAD src0_sel:WORD_1
	v_cvt_f32_f16_e32 v92, v197
	v_cvt_f32_f16_sdwa v93, v197 dst_sel:DWORD dst_unused:UNUSED_PAD src0_sel:WORD_1
	v_cvt_f32_f16_sdwa v99, v199 dst_sel:DWORD dst_unused:UNUSED_PAD src0_sel:WORD_1
	v_cvt_f32_f16_sdwa v97, v198 dst_sel:DWORD dst_unused:UNUSED_PAD src0_sel:WORD_1
	v_pk_fma_f32 v[86:87], v[86:87], v[134:135], v[90:91]
	v_pk_fma_f32 v[88:89], v[88:89], v[136:137], v[92:93]
	v_pk_fma_f32 v[90:91], v[84:85], v[132:133], v[98:99]
	v_pk_fma_f32 v[84:85], v[82:83], v[130:131], v[96:97]
	v_cvt_pk_f16_f32 v82, v86, v87
	v_cvt_pk_f16_f32 v83, v88, v89
	v_cvt_pk_f16_f32 v84, v84, v85
	v_cvt_pk_f16_f32 v85, v90, v91
	global_store_dwordx4 v[94:95], v[82:85], off offset:256 sc1
	v_cvt_f32_f16_e32 v86, v202
	v_cvt_f32_f16_e32 v88, v203
	v_cvt_f32_f16_e32 v82, v200
	v_cvt_f32_f16_sdwa v83, v200 dst_sel:DWORD dst_unused:UNUSED_PAD src0_sel:WORD_1
	v_cvt_f32_f16_e32 v84, v201
	v_cvt_f32_f16_sdwa v85, v201 dst_sel:DWORD dst_unused:UNUSED_PAD src0_sel:WORD_1
	v_cvt_f32_f16_sdwa v89, v203 dst_sel:DWORD dst_unused:UNUSED_PAD src0_sel:WORD_1
	v_cvt_f32_f16_sdwa v87, v202 dst_sel:DWORD dst_unused:UNUSED_PAD src0_sel:WORD_1
	v_pk_fma_f32 v[78:79], v[78:79], v[142:143], v[82:83]
	v_pk_fma_f32 v[80:81], v[80:81], v[144:145], v[84:85]
	v_pk_fma_f32 v[82:83], v[76:77], v[140:141], v[88:89]
	v_pk_fma_f32 v[76:77], v[74:75], v[138:139], v[86:87]
	v_cvt_pk_f16_f32 v74, v78, v79
	v_lshl_add_u64 v[78:79], s[10:11], 0, v[168:169]
	v_cvt_pk_f16_f32 v75, v80, v81
	v_cvt_pk_f16_f32 v76, v76, v77
	v_cvt_pk_f16_f32 v77, v82, v83
	v_lshl_add_u64 v[78:79], v[78:79], 0, v[162:163]
	global_store_dwordx4 v[78:79], v[74:77], off sc1
	v_cvt_f32_f16_e32 v80, v206
	v_cvt_f32_f16_e32 v82, v207
	v_cvt_f32_f16_e32 v74, v204
	v_cvt_f32_f16_sdwa v75, v204 dst_sel:DWORD dst_unused:UNUSED_PAD src0_sel:WORD_1
	v_cvt_f32_f16_e32 v76, v205
	v_cvt_f32_f16_sdwa v77, v205 dst_sel:DWORD dst_unused:UNUSED_PAD src0_sel:WORD_1
	v_cvt_f32_f16_sdwa v83, v207 dst_sel:DWORD dst_unused:UNUSED_PAD src0_sel:WORD_1
	v_cvt_f32_f16_sdwa v81, v206 dst_sel:DWORD dst_unused:UNUSED_PAD src0_sel:WORD_1
	v_pk_fma_f32 v[70:71], v[70:71], v[134:135], v[74:75]
	v_pk_fma_f32 v[72:73], v[72:73], v[136:137], v[76:77]
	v_pk_fma_f32 v[74:75], v[68:69], v[132:133], v[82:83]
	v_pk_fma_f32 v[68:69], v[66:67], v[130:131], v[80:81]
	v_cvt_pk_f16_f32 v66, v70, v71
	v_cvt_pk_f16_f32 v67, v72, v73
	v_cvt_pk_f16_f32 v68, v68, v69
	v_cvt_pk_f16_f32 v69, v74, v75
	global_store_dwordx4 v[78:79], v[66:69], off offset:256 sc1
	v_lshl_add_u64 v[98:99], v[166:167], 0, s[8:9]
	v_lshl_add_u64 v[100:101], v[166:167], 0, s[16:17]
	v_lshl_add_u64 v[66:67], v[164:165], 0, v[98:99]
	global_load_dwordx4 v[70:73], v[66:67], off nt
	global_load_dwordx4 v[74:77], v[66:67], off offset:256 nt
	v_lshl_add_u64 v[66:67], v[164:165], 0, v[100:101]
	global_load_dwordx4 v[78:81], v[66:67], off nt
	global_load_dwordx4 v[82:85], v[66:67], off offset:256 nt
	v_lshl_add_u64 v[102:103], v[166:167], 0, s[18:19]
	v_lshl_add_u64 v[66:67], v[164:165], 0, v[102:103]
	global_load_dwordx4 v[86:89], v[66:67], off nt
	global_load_dwordx4 v[90:93], v[66:67], off offset:256 nt
	v_lshl_add_u64 v[104:105], v[166:167], 0, s[20:21]
	v_lshl_add_u64 v[66:67], v[164:165], 0, v[104:105]
	global_load_dwordx4 v[94:97], v[66:67], off nt
	s_nop 0
	global_load_dwordx4 v[66:69], v[66:67], off offset:256 nt
	s_waitcnt vmcnt(7)
	v_cvt_f32_f16_e32 v106, v70
	v_cvt_f32_f16_sdwa v107, v70 dst_sel:DWORD dst_unused:UNUSED_PAD src0_sel:WORD_1
	v_cvt_f32_f16_e32 v70, v71
	v_cvt_f32_f16_sdwa v71, v71 dst_sel:DWORD dst_unused:UNUSED_PAD src0_sel:WORD_1
	v_cvt_f32_f16_e32 v108, v72
	v_cvt_f32_f16_e32 v110, v73
	v_cvt_f32_f16_sdwa v111, v73 dst_sel:DWORD dst_unused:UNUSED_PAD src0_sel:WORD_1
	v_cvt_f32_f16_sdwa v109, v72 dst_sel:DWORD dst_unused:UNUSED_PAD src0_sel:WORD_1
	v_pk_fma_f32 v[62:63], v[62:63], v[142:143], v[106:107]
	v_pk_fma_f32 v[64:65], v[64:65], v[144:145], v[70:71]
	v_pk_fma_f32 v[70:71], v[60:61], v[140:141], v[110:111]
	v_pk_fma_f32 v[60:61], v[58:59], v[138:139], v[108:109]
	v_cvt_pk_f16_f32 v58, v62, v63
	v_lshl_add_u64 v[62:63], s[10:11], 0, v[98:99]
	v_cvt_pk_f16_f32 v59, v64, v65
	v_cvt_pk_f16_f32 v60, v60, v61
	v_cvt_pk_f16_f32 v61, v70, v71
	v_lshl_add_u64 v[62:63], v[62:63], 0, v[162:163]
	global_store_dwordx4 v[62:63], v[58:61], off sc1
	s_waitcnt vmcnt(7)
	v_cvt_f32_f16_e32 v64, v76
	v_cvt_f32_f16_e32 v70, v77
	v_cvt_f32_f16_e32 v58, v74
	v_cvt_f32_f16_sdwa v59, v74 dst_sel:DWORD dst_unused:UNUSED_PAD src0_sel:WORD_1
	v_cvt_f32_f16_e32 v60, v75
	v_cvt_f32_f16_sdwa v61, v75 dst_sel:DWORD dst_unused:UNUSED_PAD src0_sel:WORD_1
	v_cvt_f32_f16_sdwa v71, v77 dst_sel:DWORD dst_unused:UNUSED_PAD src0_sel:WORD_1
	v_cvt_f32_f16_sdwa v65, v76 dst_sel:DWORD dst_unused:UNUSED_PAD src0_sel:WORD_1
	v_pk_fma_f32 v[54:55], v[54:55], v[134:135], v[58:59]
	v_pk_fma_f32 v[56:57], v[56:57], v[136:137], v[60:61]
	v_pk_fma_f32 v[58:59], v[52:53], v[132:133], v[70:71]
	v_pk_fma_f32 v[52:53], v[50:51], v[130:131], v[64:65]
	v_cvt_pk_f16_f32 v50, v54, v55
	v_cvt_pk_f16_f32 v51, v56, v57
	v_cvt_pk_f16_f32 v52, v52, v53
	v_cvt_pk_f16_f32 v53, v58, v59
	global_store_dwordx4 v[62:63], v[50:53], off offset:256 sc1
	s_waitcnt vmcnt(7)
	v_cvt_f32_f16_e32 v54, v80
	v_cvt_f32_f16_e32 v56, v81
	v_cvt_f32_f16_e32 v50, v78
	v_cvt_f32_f16_sdwa v51, v78 dst_sel:DWORD dst_unused:UNUSED_PAD src0_sel:WORD_1
	v_cvt_f32_f16_e32 v52, v79
	v_cvt_f32_f16_sdwa v53, v79 dst_sel:DWORD dst_unused:UNUSED_PAD src0_sel:WORD_1
	v_cvt_f32_f16_sdwa v57, v81 dst_sel:DWORD dst_unused:UNUSED_PAD src0_sel:WORD_1
	v_cvt_f32_f16_sdwa v55, v80 dst_sel:DWORD dst_unused:UNUSED_PAD src0_sel:WORD_1
	v_pk_fma_f32 v[46:47], v[46:47], v[142:143], v[50:51]
	v_pk_fma_f32 v[48:49], v[48:49], v[144:145], v[52:53]
	v_pk_fma_f32 v[50:51], v[44:45], v[140:141], v[56:57]
	v_pk_fma_f32 v[44:45], v[42:43], v[138:139], v[54:55]
	v_cvt_pk_f16_f32 v42, v46, v47
	v_lshl_add_u64 v[46:47], s[10:11], 0, v[100:101]
	v_cvt_pk_f16_f32 v43, v48, v49
	v_cvt_pk_f16_f32 v44, v44, v45
	v_cvt_pk_f16_f32 v45, v50, v51
	v_lshl_add_u64 v[46:47], v[46:47], 0, v[162:163]
	global_store_dwordx4 v[46:47], v[42:45], off sc1
	s_waitcnt vmcnt(7)
	v_cvt_f32_f16_e32 v48, v84
	v_cvt_f32_f16_e32 v50, v85
	v_cvt_f32_f16_e32 v42, v82
	v_cvt_f32_f16_sdwa v43, v82 dst_sel:DWORD dst_unused:UNUSED_PAD src0_sel:WORD_1
	v_cvt_f32_f16_e32 v44, v83
	v_cvt_f32_f16_sdwa v45, v83 dst_sel:DWORD dst_unused:UNUSED_PAD src0_sel:WORD_1
	v_cvt_f32_f16_sdwa v51, v85 dst_sel:DWORD dst_unused:UNUSED_PAD src0_sel:WORD_1
	v_cvt_f32_f16_sdwa v49, v84 dst_sel:DWORD dst_unused:UNUSED_PAD src0_sel:WORD_1
	v_pk_fma_f32 v[38:39], v[38:39], v[134:135], v[42:43]
	v_pk_fma_f32 v[40:41], v[40:41], v[136:137], v[44:45]
	v_pk_fma_f32 v[42:43], v[36:37], v[132:133], v[50:51]
	v_pk_fma_f32 v[36:37], v[34:35], v[130:131], v[48:49]
	v_cvt_pk_f16_f32 v34, v38, v39
	v_cvt_pk_f16_f32 v35, v40, v41
	v_cvt_pk_f16_f32 v36, v36, v37
	v_cvt_pk_f16_f32 v37, v42, v43
	global_store_dwordx4 v[46:47], v[34:37], off offset:256 sc1
	s_waitcnt vmcnt(7)
	v_cvt_f32_f16_e32 v38, v88
	v_cvt_f32_f16_e32 v40, v89
	v_cvt_f32_f16_e32 v34, v86
	v_cvt_f32_f16_sdwa v35, v86 dst_sel:DWORD dst_unused:UNUSED_PAD src0_sel:WORD_1
	v_cvt_f32_f16_e32 v36, v87
	v_cvt_f32_f16_sdwa v37, v87 dst_sel:DWORD dst_unused:UNUSED_PAD src0_sel:WORD_1
	v_cvt_f32_f16_sdwa v41, v89 dst_sel:DWORD dst_unused:UNUSED_PAD src0_sel:WORD_1
	v_cvt_f32_f16_sdwa v39, v88 dst_sel:DWORD dst_unused:UNUSED_PAD src0_sel:WORD_1
	v_pk_fma_f32 v[30:31], v[30:31], v[142:143], v[34:35]
	v_pk_fma_f32 v[32:33], v[32:33], v[144:145], v[36:37]
	v_pk_fma_f32 v[34:35], v[28:29], v[140:141], v[40:41]
	v_pk_fma_f32 v[28:29], v[26:27], v[138:139], v[38:39]
	v_cvt_pk_f16_f32 v26, v30, v31
	v_lshl_add_u64 v[30:31], s[10:11], 0, v[102:103]
	v_cvt_pk_f16_f32 v27, v32, v33
	v_cvt_pk_f16_f32 v28, v28, v29
	v_cvt_pk_f16_f32 v29, v34, v35
	v_lshl_add_u64 v[30:31], v[30:31], 0, v[162:163]
	global_store_dwordx4 v[30:31], v[26:29], off sc1
	s_waitcnt vmcnt(7)
	v_cvt_f32_f16_e32 v32, v92
	v_cvt_f32_f16_e32 v34, v93
	v_cvt_f32_f16_e32 v26, v90
	v_cvt_f32_f16_sdwa v27, v90 dst_sel:DWORD dst_unused:UNUSED_PAD src0_sel:WORD_1
	v_cvt_f32_f16_e32 v28, v91
	v_cvt_f32_f16_sdwa v29, v91 dst_sel:DWORD dst_unused:UNUSED_PAD src0_sel:WORD_1
	v_cvt_f32_f16_sdwa v35, v93 dst_sel:DWORD dst_unused:UNUSED_PAD src0_sel:WORD_1
	v_cvt_f32_f16_sdwa v33, v92 dst_sel:DWORD dst_unused:UNUSED_PAD src0_sel:WORD_1
	v_pk_fma_f32 v[22:23], v[22:23], v[134:135], v[26:27]
	v_pk_fma_f32 v[24:25], v[24:25], v[136:137], v[28:29]
	v_pk_fma_f32 v[26:27], v[20:21], v[132:133], v[34:35]
	v_pk_fma_f32 v[20:21], v[18:19], v[130:131], v[32:33]
	v_cvt_pk_f16_f32 v18, v22, v23
	v_cvt_pk_f16_f32 v19, v24, v25
	v_cvt_pk_f16_f32 v20, v20, v21
	v_cvt_pk_f16_f32 v21, v26, v27
	global_store_dwordx4 v[30:31], v[18:21], off offset:256 sc1
	s_waitcnt vmcnt(7)
	v_cvt_f32_f16_e32 v22, v96
	v_cvt_f32_f16_e32 v24, v97
	v_cvt_f32_f16_e32 v18, v94
	v_cvt_f32_f16_sdwa v19, v94 dst_sel:DWORD dst_unused:UNUSED_PAD src0_sel:WORD_1
	v_cvt_f32_f16_e32 v20, v95
	v_cvt_f32_f16_sdwa v21, v95 dst_sel:DWORD dst_unused:UNUSED_PAD src0_sel:WORD_1
	v_cvt_f32_f16_sdwa v25, v97 dst_sel:DWORD dst_unused:UNUSED_PAD src0_sel:WORD_1
	v_cvt_f32_f16_sdwa v23, v96 dst_sel:DWORD dst_unused:UNUSED_PAD src0_sel:WORD_1
	v_pk_fma_f32 v[14:15], v[14:15], v[142:143], v[18:19]
	v_pk_fma_f32 v[16:17], v[16:17], v[144:145], v[20:21]
	v_pk_fma_f32 v[18:19], v[12:13], v[140:141], v[24:25]
	v_pk_fma_f32 v[12:13], v[10:11], v[138:139], v[22:23]
	v_cvt_pk_f16_f32 v10, v14, v15
	v_lshl_add_u64 v[14:15], s[10:11], 0, v[104:105]
	v_cvt_pk_f16_f32 v11, v16, v17
	v_cvt_pk_f16_f32 v12, v12, v13
	v_cvt_pk_f16_f32 v13, v18, v19
	v_lshl_add_u64 v[14:15], v[14:15], 0, v[162:163]
	global_store_dwordx4 v[14:15], v[10:13], off sc1
	s_waitcnt vmcnt(7)
	v_cvt_f32_f16_e32 v16, v68
	v_cvt_f32_f16_e32 v18, v69
	v_cvt_f32_f16_e32 v10, v66
	v_cvt_f32_f16_sdwa v11, v66 dst_sel:DWORD dst_unused:UNUSED_PAD src0_sel:WORD_1
	v_cvt_f32_f16_e32 v12, v67
	v_cvt_f32_f16_sdwa v13, v67 dst_sel:DWORD dst_unused:UNUSED_PAD src0_sel:WORD_1
	v_cvt_f32_f16_sdwa v19, v69 dst_sel:DWORD dst_unused:UNUSED_PAD src0_sel:WORD_1
	v_cvt_f32_f16_sdwa v17, v68 dst_sel:DWORD dst_unused:UNUSED_PAD src0_sel:WORD_1
	v_pk_fma_f32 v[6:7], v[6:7], v[134:135], v[10:11]
	v_pk_fma_f32 v[8:9], v[8:9], v[136:137], v[12:13]
	v_pk_fma_f32 v[10:11], v[4:5], v[132:133], v[18:19]
	v_pk_fma_f32 v[4:5], v[2:3], v[130:131], v[16:17]
	v_cvt_pk_f16_f32 v2, v6, v7
	v_cvt_pk_f16_f32 v3, v8, v9
	v_cvt_pk_f16_f32 v4, v4, v5
	v_cvt_pk_f16_f32 v5, v10, v11
	global_store_dwordx4 v[14:15], v[2:5], off offset:256 sc1
	s_cbranch_vccnz .LBB0_849
	s_andn2_b64 vcc, exec, s[6:7]
	s_cbranch_vccnz .LBB0_848
	s_barrier
	s_branch .LBB0_848

.LBB0_864:
	v_readlane_b32 s0, v254, 0
	v_readlane_b32 s1, v254, 1
	s_cmp_gt_i32 s1, 9
	s_cselect_b64 s[0:1], -1, 0
	s_and_b64 s[4:5], s[4:5], s[0:1]
	s_andn2_b64 vcc, exec, s[4:5]
	s_cbranch_vccnz .LBB0_918
	s_waitcnt vmcnt(0)
	s_waitcnt vmcnt(0)
	s_barrier
	s_mov_b64 s[4:5], exec
	v_readlane_b32 s6, v254, 7
	v_readlane_b32 s7, v254, 8
	s_and_b64 s[6:7], s[4:5], s[6:7]
	s_mov_b64 exec, s[6:7]
	s_cbranch_execz .Lmy_cv8_entry
	s_cmpk_lg_i32 s3, 0x100
	s_cbranch_scc1 .Lmy_gb8_orig
	s_and_b32 s6, s2, 7
	s_lshl_b32 s6, s6, 6
	s_add_u32 s6, s6, 0x34400
	v_mov_b32_e32 v2, s6
	v_mov_b32_e32 v3, 1
	global_atomic_add v2, v3, s[50:51]
	s_movk_i32 s7, 0x4000

.LBB0_918:
	v_readlane_b32 s4, v254, 0
	v_readlane_b32 s5, v254, 1
	s_cmp_lt_i32 s4, 10
	s_cselect_b64 s[4:5], -1, 0
	s_and_b64 s[4:5], s[4:5], s[0:1]
	s_andn2_b64 vcc, exec, s[4:5]
	s_cbranch_vccnz .LBB0_922
	s_cmpk_gt_i32 s70, 0x1fff
	s_cbranch_scc1 .LBB0_922
	s_mov_b32 s98, s70
	s_movk_i32 s100, 0x2000
	s_mov_b32 s101, s72
	s_cmpk_lg_i32 s3, 0x100
	s_cbranch_scc1 .Lmy_gr9
	s_and_b32 s98, s2, 7
	s_lshl_b32 s98, s98, 10
	s_add_i32 s100, s98, 0x400
	s_lshr_b32 s99, s2, 3
	s_lshl_b32 s99, s99, 3
	s_add_i32 s98, s98, s99
	v_readlane_b32 s99, v254, 10
	s_add_i32 s98, s98, s99
	s_movk_i32 s101, 0x100
.Lmy_gr9:
	s_mov_b32 s99, 0
	v_lshlrev_b32_e32 v36, 3, v1
	v_lshlrev_b32_e32 v18, 5, v1
	global_load_dwordx4 v[2:5], v18, s[40:41] offset:16
	global_load_dwordx4 v[6:9], v18, s[40:41]
	global_load_dwordx4 v[10:13], v18, s[40:41] offset:2064
	global_load_dwordx4 v[14:17], v18, s[40:41] offset:2048
	v_or_b32_e32 v38, 0x400, v36
	v_or_b32_e32 v40, 0x600, v36
	v_lshlrev_b32_e32 v26, 2, v38
	v_lshlrev_b32_e32 v34, 2, v40
	global_load_dwordx4 v[18:21], v26, s[40:41] offset:16
	global_load_dwordx4 v[22:25], v26, s[40:41]
	s_nop 0
	global_load_dwordx4 v[26:29], v34, s[40:41] offset:16
	global_load_dwordx4 v[30:33], v34, s[40:41]
	v_mbcnt_lo_u32_b32 v34, -1, 0
	v_mbcnt_hi_u32_b32 v34, -1, v34
	v_and_b32_e32 v35, 64, v34
	v_add_u32_e32 v35, 64, v35
	v_xor_b32_e32 v37, 1, v34
	v_cmp_lt_i32_e32 vcc, v37, v35
	s_ashr_i32 s71, s70, 31
	s_lshl_b64 s[0:1], s[98:99], 12
	v_cndmask_b32_e32 v37, v34, v37, vcc
	v_lshlrev_b32_e32 v44, 2, v37
	v_xor_b32_e32 v37, 2, v34
	v_cmp_lt_i32_e32 vcc, v37, v35
	s_add_u32 s0, s50, s0
	s_addc_u32 s1, s51, s1
	v_cndmask_b32_e32 v37, v34, v37, vcc
	v_lshlrev_b32_e32 v45, 2, v37
	v_xor_b32_e32 v37, 4, v34
	v_cmp_lt_i32_e32 vcc, v37, v35
	v_or_b32_e32 v42, 0x200, v36
	s_ashr_i32 s73, s72, 31
	v_cndmask_b32_e32 v37, v34, v37, vcc
	v_lshlrev_b32_e32 v46, 2, v37
	v_xor_b32_e32 v37, 8, v34
	v_cmp_lt_i32_e32 vcc, v37, v35
	v_mov_b32_e32 v50, 0x358637bd
	v_lshlrev_b32_e32 v51, 2, v36
	v_cndmask_b32_e32 v37, v34, v37, vcc
	v_lshlrev_b32_e32 v47, 2, v37
	v_xor_b32_e32 v37, 16, v34
	v_cmp_lt_i32_e32 vcc, v37, v35
	s_mov_b32 s10, 0xee800000
	v_lshlrev_b32_e32 v52, 2, v42
	v_cndmask_b32_e32 v37, v34, v37, vcc
	v_lshlrev_b32_e32 v48, 2, v37
	v_xor_b32_e32 v37, 32, v34
	v_cmp_lt_i32_e32 vcc, v37, v35
	v_mov_b32_e32 v35, 0
	s_mov_b32 s11, 0xee801000
	v_cndmask_b32_e32 v34, v34, v37, vcc
	v_lshlrev_b32_e32 v49, 2, v34
	v_lshlrev_b32_e32 v34, 4, v1
	v_lshl_add_u64 v[34:35], s[0:1], 0, v[34:35]
	s_mov_b64 s[0:1], 0x1c400000
	v_lshl_add_u64 v[34:35], v[34:35], 0, s[0:1]
	s_lshl_b32 s0, s101, 12
	s_mov_b32 s1, 0
	v_lshlrev_b32_e32 v53, 2, v38
	v_lshlrev_b32_e32 v54, 2, v40
.LBB0_921:
	global_load_dwordx4 v[36:39], v[34:35], off nt
	global_load_dwordx4 v[40:43], v[34:35], off offset:1024 nt
	global_load_dwordx4 v[56:59], v[34:35], off offset:2048 nt
	global_load_dwordx4 v[60:63], v[34:35], off offset:3072 nt
	s_ashr_i32 s6, s98, 12
	s_mul_hi_i32 s7, s6, 0x12000
	s_mul_i32 s6, s6, 0x12000
	s_add_u32 s8, s50, s6
	s_addc_u32 s9, s51, s7
	s_add_u32 s6, s8, 0xc000
	s_addc_u32 s7, s9, 0
	s_add_u32 s8, s8, 0xe000
	s_addc_u32 s9, s9, 0
	global_load_dwordx4 v[64:67], v51, s[6:7] offset:16
	global_load_dwordx4 v[68:71], v51, s[6:7]
	global_load_dwordx4 v[72:75], v51, s[8:9] offset:16
	global_load_dwordx4 v[76:79], v51, s[8:9]
	v_add_co_u32_e32 v80, vcc, s10, v34
	s_add_i32 s98, s98, s101
	s_nop 0
	v_addc_co_u32_e32 v81, vcc, -1, v35, vcc
	s_cmp_lt_i32 s98, s100
	s_waitcnt vmcnt(0)
	v_cvt_f32_f16_sdwa v83, v36 dst_sel:DWORD dst_unused:UNUSED_PAD src0_sel:WORD_1
	v_cvt_f32_f16_sdwa v85, v37 dst_sel:DWORD dst_unused:UNUSED_PAD src0_sel:WORD_1
	v_cvt_f32_f16_sdwa v87, v38 dst_sel:DWORD dst_unused:UNUSED_PAD src0_sel:WORD_1
	v_cvt_f32_f16_sdwa v89, v39 dst_sel:DWORD dst_unused:UNUSED_PAD src0_sel:WORD_1
	v_cvt_f32_f16_e32 v82, v36
	v_cvt_f32_f16_e32 v84, v37
	v_cvt_f32_f16_e32 v86, v38
	v_cvt_f32_f16_e32 v88, v39
	v_cvt_f32_f16_sdwa v91, v40 dst_sel:DWORD dst_unused:UNUSED_PAD src0_sel:WORD_1
	v_cvt_f32_f16_sdwa v93, v41 dst_sel:DWORD dst_unused:UNUSED_PAD src0_sel:WORD_1
	v_cvt_f32_f16_e32 v90, v40
	v_cvt_f32_f16_e32 v92, v41
	v_cvt_f32_f16_e32 v94, v42
	v_cvt_f32_f16_e32 v96, v43
	v_cvt_f32_f16_sdwa v95, v42 dst_sel:DWORD dst_unused:UNUSED_PAD src0_sel:WORD_1
	v_cvt_f32_f16_sdwa v97, v43 dst_sel:DWORD dst_unused:UNUSED_PAD src0_sel:WORD_1
	v_cvt_f32_f16_sdwa v99, v56 dst_sel:DWORD dst_unused:UNUSED_PAD src0_sel:WORD_1
	v_cvt_f32_f16_e32 v98, v56
	v_cvt_f32_f16_sdwa v101, v57 dst_sel:DWORD dst_unused:UNUSED_PAD src0_sel:WORD_1
	v_cvt_f32_f16_e32 v100, v57
	v_cvt_f32_f16_sdwa v103, v58 dst_sel:DWORD dst_unused:UNUSED_PAD src0_sel:WORD_1
	v_cvt_f32_f16_e32 v102, v58
	v_cvt_f32_f16_sdwa v105, v59 dst_sel:DWORD dst_unused:UNUSED_PAD src0_sel:WORD_1
	v_cvt_f32_f16_e32 v104, v59
	v_cvt_f32_f16_sdwa v39, v62 dst_sel:DWORD dst_unused:UNUSED_PAD src0_sel:WORD_1
	v_cvt_f32_f16_e32 v38, v62
	v_cvt_f32_f16_sdwa v43, v63 dst_sel:DWORD dst_unused:UNUSED_PAD src0_sel:WORD_1
	v_cvt_f32_f16_e32 v42, v63
	v_mov_b32_e32 v58, v83
	v_mov_b32_e32 v59, v87
	v_mov_b32_e32 v62, v85
	v_mov_b32_e32 v63, v89
	v_cvt_f32_f16_sdwa v37, v60 dst_sel:DWORD dst_unused:UNUSED_PAD src0_sel:WORD_1
	v_cvt_f32_f16_e32 v36, v60
	v_cvt_f32_f16_sdwa v41, v61 dst_sel:DWORD dst_unused:UNUSED_PAD src0_sel:WORD_1
	v_cvt_f32_f16_e32 v40, v61
	v_mov_b32_e32 v56, v82
	v_mov_b32_e32 v57, v86
	v_mov_b32_e32 v60, v84
	v_mov_b32_e32 v61, v88
	v_mov_b32_e32 v108, v91
	v_mov_b32_e32 v109, v93
	v_pk_mul_f32 v[58:59], v[58:59], v[58:59]
	v_pk_mul_f32 v[62:63], v[62:63], v[62:63]
	v_mov_b32_e32 v106, v90
	v_mov_b32_e32 v107, v92
	v_pk_mul_f32 v[108:109], v[108:109], v[108:109]
	v_pk_fma_f32 v[56:57], v[56:57], v[56:57], v[58:59]
	v_pk_fma_f32 v[58:59], v[60:61], v[60:61], v[62:63]
	v_mul_f32_e32 v110, v94, v94
	v_mul_f32_e32 v112, v96, v96
	v_pk_fma_f32 v[60:61], v[106:107], v[106:107], v[108:109]
	v_pk_add_f32 v[56:57], v[56:57], v[58:59]
	v_pk_mul_f32 v[114:115], v[98:99], v[98:99]
	v_pk_mul_f32 v[116:117], v[100:101], v[100:101]
	v_pk_fma_f32 v[110:111], v[94:95], v[94:95], v[110:111] op_sel_hi:[1,1,0]
	v_pk_fma_f32 v[112:113], v[96:97], v[96:97], v[112:113] op_sel_hi:[1,1,0]
	v_pk_add_f32 v[58:59], v[60:61], v[60:61] op_sel_hi:[0,1]
	v_pk_add_f32 v[56:57], v[56:57], v[56:57] op_sel_hi:[0,1]
	v_mov_b32_e32 v120, v103
	v_mov_b32_e32 v121, v105
	v_mov_b32_e32 v110, v114
	v_mov_b32_e32 v112, v115
	v_mov_b32_e32 v58, v117
	v_mov_b32_e32 v56, v116
	v_mov_b32_e32 v118, v102
	v_mov_b32_e32 v119, v104
	v_pk_mul_f32 v[120:121], v[120:121], v[120:121]
	v_pk_add_f32 v[60:61], v[110:111], v[112:113]
	v_pk_add_f32 v[56:57], v[56:57], v[58:59]
	v_mul_f32_e32 v122, v36, v36
	v_mul_f32_e32 v124, v40, v40
	v_pk_fma_f32 v[62:63], v[118:119], v[118:119], v[120:121]
	v_pk_add_f32 v[56:57], v[60:61], v[56:57]
	v_pk_mul_f32 v[126:127], v[38:39], v[38:39]
	v_pk_mul_f32 v[128:129], v[42:43], v[42:43]
	v_pk_fma_f32 v[122:123], v[36:37], v[36:37], v[122:123] op_sel_hi:[1,1,0]
	v_pk_fma_f32 v[124:125], v[40:41], v[40:41], v[124:125] op_sel_hi:[1,1,0]
	v_pk_add_f32 v[62:63], v[62:63], v[62:63] op_sel_hi:[0,1]
	v_pk_add_f32 v[56:57], v[56:57], v[56:57] op_sel_hi:[0,1]
	v_mov_b32_e32 v122, v126
	v_mov_b32_e32 v124, v127
	v_mov_b32_e32 v62, v128
	v_mov_b32_e32 v56, v129
	v_pk_add_f32 v[106:107], v[122:123], v[124:125]
	v_pk_add_f32 v[56:57], v[62:63], v[56:57]
	v_pk_add_f32 v[78:79], v[78:79], 1.0 op_sel_hi:[1,0]
	v_pk_add_f32 v[56:57], v[106:107], v[56:57]
	v_pk_add_f32 v[76:77], v[76:77], 1.0 op_sel_hi:[1,0]
	v_add_f32_e32 v55, v56, v57
	ds_bpermute_b32 v56, v44, v55
	v_pk_add_f32 v[74:75], v[74:75], 1.0 op_sel_hi:[1,0]
	v_pk_add_f32 v[72:73], v[72:73], 1.0 op_sel_hi:[1,0]
	s_waitcnt lgkmcnt(0)
	v_add_f32_e32 v55, v55, v56
	ds_bpermute_b32 v56, v45, v55
	s_waitcnt lgkmcnt(0)
	v_add_f32_e32 v55, v55, v56
	ds_bpermute_b32 v56, v46, v55
	s_waitcnt lgkmcnt(0)
	v_add_f32_e32 v55, v55, v56
	ds_bpermute_b32 v56, v47, v55
	s_waitcnt lgkmcnt(0)
	v_add_f32_e32 v55, v55, v56
	ds_bpermute_b32 v56, v48, v55
	s_waitcnt lgkmcnt(0)
	v_add_f32_e32 v55, v55, v56
	ds_bpermute_b32 v56, v49, v55
	s_waitcnt lgkmcnt(0)
	v_add_f32_e32 v55, v55, v56
	v_fmamk_f32 v55, v55, 0x3a000000, v50
	v_rsq_f32_e32 v106, v55
	s_nop 0
	v_pk_mul_f32 v[56:57], v[84:85], v[106:107] op_sel_hi:[1,0]
	v_pk_mul_f32 v[58:59], v[82:83], v[106:107] op_sel_hi:[1,0]
	v_pk_mul_f32 v[60:61], v[88:89], v[106:107] op_sel_hi:[1,0]
	v_pk_mul_f32 v[62:63], v[86:87], v[106:107] op_sel_hi:[1,0]
	v_pk_mul_f32 v[58:59], v[6:7], v[58:59]
	v_pk_mul_f32 v[56:57], v[8:9], v[56:57]
	v_pk_mul_f32 v[62:63], v[2:3], v[62:63]
	v_pk_mul_f32 v[60:61], v[4:5], v[60:61]
	v_pk_fma_f32 v[70:71], v[78:79], v[56:57], v[70:71]
	v_pk_fma_f32 v[56:57], v[76:77], v[58:59], v[68:69]
	v_pk_fma_f32 v[60:61], v[74:75], v[60:61], v[66:67]
	v_pk_fma_f32 v[58:59], v[72:73], v[62:63], v[64:65]
	v_cvt_pk_bf16_f32 v56, v56, v57
	v_cvt_pk_bf16_f32 v57, v70, v71
	v_cvt_pk_bf16_f32 v58, v58, v59
	v_cvt_pk_bf16_f32 v59, v60, v61
	global_store_dwordx4 v[80:81], v[56:59], off
	global_load_dwordx4 v[56:59], v52, s[8:9]
	s_nop 0
	global_load_dwordx4 v[60:63], v52, s[8:9] offset:16
	global_load_dwordx4 v[64:67], v52, s[6:7]
	global_load_dwordx4 v[68:71], v52, s[6:7] offset:16
	v_pk_mul_f32 v[74:75], v[92:93], v[106:107] op_sel_hi:[1,0]
	v_pk_mul_f32 v[76:77], v[90:91], v[106:107] op_sel_hi:[1,0]
	v_pk_mul_f32 v[78:79], v[96:97], v[106:107] op_sel_hi:[1,0]
	v_pk_mul_f32 v[80:81], v[94:95], v[106:107] op_sel_hi:[1,0]
	v_pk_mul_f32 v[76:77], v[14:15], v[76:77]
	v_pk_mul_f32 v[74:75], v[16:17], v[74:75]
	v_pk_mul_f32 v[80:81], v[10:11], v[80:81]
	v_pk_mul_f32 v[78:79], v[12:13], v[78:79]
	v_add_co_u32_e32 v72, vcc, s11, v34
	v_pk_mul_f32 v[40:41], v[40:41], v[106:107] op_sel_hi:[1,0]
	s_nop 0
	v_addc_co_u32_e32 v73, vcc, -1, v35, vcc
	v_pk_mul_f32 v[36:37], v[36:37], v[106:107] op_sel_hi:[1,0]
	v_pk_mul_f32 v[42:43], v[42:43], v[106:107] op_sel_hi:[1,0]
	v_pk_mul_f32 v[38:39], v[38:39], v[106:107] op_sel_hi:[1,0]
	v_pk_mul_f32 v[36:37], v[30:31], v[36:37]
	v_pk_mul_f32 v[40:41], v[32:33], v[40:41]
	v_pk_mul_f32 v[38:39], v[26:27], v[38:39]
	v_pk_mul_f32 v[42:43], v[28:29], v[42:43]
	v_lshl_add_u64 v[34:35], v[34:35], 0, s[0:1]
	s_waitcnt vmcnt(3)
	v_pk_add_f32 v[58:59], v[58:59], 1.0 op_sel_hi:[1,0]
	v_pk_add_f32 v[56:57], v[56:57], 1.0 op_sel_hi:[1,0]
	s_waitcnt vmcnt(2)
	v_pk_add_f32 v[62:63], v[62:63], 1.0 op_sel_hi:[1,0]
	v_pk_add_f32 v[60:61], v[60:61], 1.0 op_sel_hi:[1,0]
	s_waitcnt vmcnt(1)
	v_pk_fma_f32 v[58:59], v[58:59], v[74:75], v[66:67]
	v_pk_fma_f32 v[56:57], v[56:57], v[76:77], v[64:65]
	s_waitcnt vmcnt(0)
	v_pk_fma_f32 v[62:63], v[62:63], v[78:79], v[70:71]
	v_pk_fma_f32 v[60:61], v[60:61], v[80:81], v[68:69]
	v_cvt_pk_bf16_f32 v56, v56, v57
	v_cvt_pk_bf16_f32 v57, v58, v59
	v_cvt_pk_bf16_f32 v58, v60, v61
	v_cvt_pk_bf16_f32 v59, v62, v63
	global_store_dwordx4 v[72:73], v[56:59], off offset:-3072
	global_load_dwordx4 v[56:59], v53, s[8:9]
	s_nop 0
	global_load_dwordx4 v[60:63], v53, s[8:9] offset:16
	global_load_dwordx4 v[64:67], v53, s[6:7]
	global_load_dwordx4 v[68:71], v53, s[6:7] offset:16
	v_pk_mul_f32 v[74:75], v[100:101], v[106:107] op_sel_hi:[1,0]
	v_pk_mul_f32 v[76:77], v[98:99], v[106:107] op_sel_hi:[1,0]
	v_pk_mul_f32 v[78:79], v[104:105], v[106:107] op_sel_hi:[1,0]
	v_pk_mul_f32 v[80:81], v[102:103], v[106:107] op_sel_hi:[1,0]
	v_pk_mul_f32 v[76:77], v[22:23], v[76:77]
	v_pk_mul_f32 v[74:75], v[24:25], v[74:75]
	v_pk_mul_f32 v[80:81], v[18:19], v[80:81]
	v_pk_mul_f32 v[78:79], v[20:21], v[78:79]
	s_waitcnt vmcnt(3)
	v_pk_add_f32 v[58:59], v[58:59], 1.0 op_sel_hi:[1,0]
	v_pk_add_f32 v[56:57], v[56:57], 1.0 op_sel_hi:[1,0]
	s_waitcnt vmcnt(2)
	v_pk_add_f32 v[62:63], v[62:63], 1.0 op_sel_hi:[1,0]
	v_pk_add_f32 v[60:61], v[60:61], 1.0 op_sel_hi:[1,0]
	s_waitcnt vmcnt(1)
	v_pk_fma_f32 v[58:59], v[58:59], v[74:75], v[66:67]
	v_pk_fma_f32 v[56:57], v[56:57], v[76:77], v[64:65]
	s_waitcnt vmcnt(0)
	v_pk_fma_f32 v[62:63], v[62:63], v[78:79], v[70:71]
	v_pk_fma_f32 v[60:61], v[60:61], v[80:81], v[68:69]
	v_cvt_pk_bf16_f32 v56, v56, v57
	v_cvt_pk_bf16_f32 v57, v58, v59
	v_cvt_pk_bf16_f32 v58, v60, v61
	v_cvt_pk_bf16_f32 v59, v62, v63
	global_store_dwordx4 v[72:73], v[56:59], off offset:-2048
	global_load_dwordx4 v[56:59], v54, s[8:9]
	s_nop 0
	global_load_dwordx4 v[60:63], v54, s[8:9] offset:16
	global_load_dwordx4 v[64:67], v54, s[6:7]
	global_load_dwordx4 v[68:71], v54, s[6:7] offset:16
	s_waitcnt vmcnt(3)
	v_pk_add_f32 v[58:59], v[58:59], 1.0 op_sel_hi:[1,0]
	v_pk_add_f32 v[56:57], v[56:57], 1.0 op_sel_hi:[1,0]
	s_waitcnt vmcnt(2)
	v_pk_add_f32 v[62:63], v[62:63], 1.0 op_sel_hi:[1,0]
	v_pk_add_f32 v[60:61], v[60:61], 1.0 op_sel_hi:[1,0]
	s_waitcnt vmcnt(1)
	v_pk_fma_f32 v[40:41], v[58:59], v[40:41], v[66:67]
	v_pk_fma_f32 v[36:37], v[56:57], v[36:37], v[64:65]
	s_waitcnt vmcnt(0)
	v_pk_fma_f32 v[42:43], v[42:43], v[62:63], v[70:71]
	v_pk_fma_f32 v[38:39], v[38:39], v[60:61], v[68:69]
	v_cvt_pk_bf16_f32 v36, v36, v37
	v_cvt_pk_bf16_f32 v37, v40, v41
	v_cvt_pk_bf16_f32 v38, v38, v39
	v_cvt_pk_bf16_f32 v39, v42, v43
	global_store_dwordx4 v[72:73], v[36:39], off offset:-1024
	s_cbranch_scc1 .LBB0_921

	.amdhsa_kernel _Z10fwd_kernel4Args
		.amdhsa_group_segment_fixed_size 0
		.amdhsa_private_segment_fixed_size 0
		.amdhsa_kernarg_size 456
		.amdhsa_user_sgpr_count 2
		.amdhsa_user_sgpr_dispatch_ptr 0
		.amdhsa_user_sgpr_queue_ptr 0
		.amdhsa_user_sgpr_kernarg_segment_ptr 1
		.amdhsa_user_sgpr_dispatch_id 0
		.amdhsa_user_sgpr_kernarg_preload_length 0
		.amdhsa_user_sgpr_kernarg_preload_offset 0
		.amdhsa_user_sgpr_private_segment_size 0
		.amdhsa_uses_dynamic_stack 0
		.amdhsa_enable_private_segment 0
		.amdhsa_system_sgpr_workgroup_id_x 1
		.amdhsa_system_sgpr_workgroup_id_y 0
		.amdhsa_system_sgpr_workgroup_id_z 0
		.amdhsa_system_sgpr_workgroup_info 0
		.amdhsa_system_vgpr_workitem_id 0
		.amdhsa_next_free_vgpr 255
		.amdhsa_next_free_sgpr 102
		.amdhsa_accum_offset 256
		.amdhsa_reserve_vcc 1
		.amdhsa_float_round_mode_32 0
		.amdhsa_float_round_mode_16_64 0
		.amdhsa_float_denorm_mode_32 3
		.amdhsa_float_denorm_mode_16_64 3
		.amdhsa_dx10_clamp 1
		.amdhsa_ieee_mode 1
		.amdhsa_fp16_overflow 0
		.amdhsa_tg_split 0
		.amdhsa_exception_fp_ieee_invalid_op 0
		.amdhsa_exception_fp_denorm_src 0
		.amdhsa_exception_fp_ieee_div_zero 0
		.amdhsa_exception_fp_ieee_overflow 0
		.amdhsa_exception_fp_ieee_underflow 0
		.amdhsa_exception_fp_ieee_inexact 0
		.amdhsa_exception_int_div_zero 0
	.end_amdhsa_kernel

amdhsa.kernels:
  - .agpr_count:     0
    .args:
      - .offset:         0
        .size:           200
        .value_kind:     by_value
      - .offset:         200
        .size:           4
        .value_kind:     hidden_block_count_x
      - .offset:         204
        .size:           4
        .value_kind:     hidden_block_count_y
      - .offset:         208
        .size:           4
        .value_kind:     hidden_block_count_z
      - .offset:         212
        .size:           2
        .value_kind:     hidden_group_size_x
      - .offset:         214
        .size:           2
        .value_kind:     hidden_group_size_y
      - .offset:         216
        .size:           2
        .value_kind:     hidden_group_size_z
      - .offset:         218
        .size:           2
        .value_kind:     hidden_remainder_x
      - .offset:         220
        .size:           2
        .value_kind:     hidden_remainder_y
      - .offset:         222
        .size:           2
        .value_kind:     hidden_remainder_z
      - .offset:         240
        .size:           8
        .value_kind:     hidden_global_offset_x
      - .offset:         248
        .size:           8
        .value_kind:     hidden_global_offset_y
      - .offset:         256
        .size:           8
        .value_kind:     hidden_global_offset_z
      - .offset:         264
        .size:           2
        .value_kind:     hidden_grid_dims
      - .offset:         320
        .size:           4
        .value_kind:     hidden_dynamic_lds_size
    .group_segment_fixed_size: 0
    .kernarg_segment_align: 8
    .kernarg_segment_size: 456
    .language:       OpenCL C
    .language_version:
      - 2
      - 0
    .max_flat_workgroup_size: 512
    .name:           _Z10fwd_kernel4Args
    .private_segment_fixed_size: 0
    .sgpr_count:     108
    .sgpr_spill_count: 16
    .symbol:         _Z10fwd_kernel4Args.kd
    .uniform_work_group_size: 1
    .uses_dynamic_stack: false
    .vgpr_count:     255
    .vgpr_spill_count: 0
    .wavefront_size: 64
